# loop-edge edit: K-loop counter and pointer-advance SALU moved from after the loop-back barrier into the MFMA shadow of the last MMA segment (all 8 GEMM K-loops), on top of m0 save/restore strip
# baseline (speedup 1.0000x reference)
.LBB0_317:
	v_add_u32_e32 v168, 0x10000, v162
	v_add_u32_e32 v184, 0x14000, v162
	ds_read_b128 v[150:153], v168
	ds_read_b128 v[154:157], v168 offset:1024
	ds_read_b128 v[164:167], v168 offset:2048
	ds_read_b128 v[168:171], v168 offset:3072
	ds_read_b128 v[172:175], v184
	ds_read_b128 v[176:179], v184 offset:1024
	ds_read_b128 v[180:183], v184 offset:2048
	ds_read_b128 v[184:187], v184 offset:3072
	s_add_i32 s33, s2, 2
	s_cmp_eq_u32 s72, s2
	s_cselect_b32 s42, s1, s14
	s_cselect_b32 s43, s0, s15
	s_cselect_b32 s40, s7, s25
	s_cselect_b32 s41, s5, s27
	s_add_u32 s2, s42, 0x80
	s_addc_u32 s3, s43, 0
	ds_read_b128 v[188:191], v163
	ds_read_b128 v[192:195], v163 offset:1024
	ds_read_b128 v[206:209], v163 offset:2048
	ds_read_b128 v[210:213], v163 offset:3072
	ds_read_b128 v[214:217], v163 offset:4096
	ds_read_b128 v[226:229], v163 offset:5120
	ds_read_b128 v[230:233], v163 offset:6144
	ds_read_b128 v[234:237], v163 offset:7168
	s_add_u32 s34, s14, 0x7ff80
	s_addc_u32 s35, s15, 0
	s_mov_b32 m0, s73
	s_nop 0
	global_load_lds_dwordx4 v149, s[34:35]
	s_mov_b32 m0, s75
	s_nop 0
	global_load_lds_dwordx4 v159, s[34:35]
	s_waitcnt vmcnt(8)
	s_waitcnt lgkmcnt(0)
	s_barrier
	s_setprio 1
	s_waitcnt lgkmcnt(7)
	v_mfma_f32_16x16x32_bf16 v[128:131], v[150:153], v[188:191], v[128:131]
	v_mfma_f32_16x16x32_bf16 v[124:127], v[164:167], v[188:191], v[124:127]
	s_waitcnt lgkmcnt(5)
	v_mfma_f32_16x16x32_bf16 v[112:115], v[150:153], v[206:209], v[112:115]
	v_mfma_f32_16x16x32_bf16 v[108:111], v[164:167], v[206:209], v[108:111]
	s_waitcnt lgkmcnt(3)
	v_mfma_f32_16x16x32_bf16 v[96:99], v[150:153], v[214:217], v[96:99]
	v_mfma_f32_16x16x32_bf16 v[92:95], v[164:167], v[214:217], v[92:95]
	s_waitcnt lgkmcnt(1)
	v_mfma_f32_16x16x32_bf16 v[80:83], v[150:153], v[230:233], v[80:83]
	v_mfma_f32_16x16x32_bf16 v[76:79], v[164:167], v[230:233], v[76:79]
	v_mfma_f32_16x16x32_bf16 v[128:131], v[154:157], v[192:195], v[128:131]
	v_mfma_f32_16x16x32_bf16 v[124:127], v[168:171], v[192:195], v[124:127]
	v_mfma_f32_16x16x32_bf16 v[112:115], v[154:157], v[210:213], v[112:115]
	v_mfma_f32_16x16x32_bf16 v[108:111], v[168:171], v[210:213], v[108:111]
	v_mfma_f32_16x16x32_bf16 v[96:99], v[154:157], v[226:229], v[96:99]
	v_mfma_f32_16x16x32_bf16 v[92:95], v[168:171], v[226:229], v[92:95]
	s_waitcnt lgkmcnt(0)
	v_mfma_f32_16x16x32_bf16 v[80:83], v[154:157], v[234:237], v[80:83]
	v_mfma_f32_16x16x32_bf16 v[76:79], v[168:171], v[234:237], v[76:79]
	s_setprio 0
	s_setprio 1
	v_mfma_f32_16x16x32_bf16 v[120:123], v[172:175], v[188:191], v[120:123]
	v_mfma_f32_16x16x32_bf16 v[116:119], v[180:183], v[188:191], v[116:119]
	v_mfma_f32_16x16x32_bf16 v[104:107], v[172:175], v[206:209], v[104:107]
	v_mfma_f32_16x16x32_bf16 v[100:103], v[180:183], v[206:209], v[100:103]
	v_mfma_f32_16x16x32_bf16 v[88:91], v[172:175], v[214:217], v[88:91]
	v_mfma_f32_16x16x32_bf16 v[84:87], v[180:183], v[214:217], v[84:87]
	v_mfma_f32_16x16x32_bf16 v[72:75], v[172:175], v[230:233], v[72:75]
	v_mfma_f32_16x16x32_bf16 v[68:71], v[180:183], v[230:233], v[68:71]
	v_mfma_f32_16x16x32_bf16 v[120:123], v[176:179], v[192:195], v[120:123]
	v_mfma_f32_16x16x32_bf16 v[116:119], v[184:187], v[192:195], v[116:119]
	v_mfma_f32_16x16x32_bf16 v[104:107], v[176:179], v[210:213], v[104:107]
	v_mfma_f32_16x16x32_bf16 v[100:103], v[184:187], v[210:213], v[100:103]
	v_mfma_f32_16x16x32_bf16 v[88:91], v[176:179], v[226:229], v[88:91]
	v_mfma_f32_16x16x32_bf16 v[84:87], v[184:187], v[226:229], v[84:87]
	v_mfma_f32_16x16x32_bf16 v[72:75], v[176:179], v[234:237], v[72:75]
	v_mfma_f32_16x16x32_bf16 v[68:71], v[184:187], v[234:237], v[68:71]
	s_setprio 0
	s_barrier
	ds_read_b128 v[188:191], v163 offset:16384
	ds_read_b128 v[192:195], v163 offset:17408
	ds_read_b128 v[206:209], v163 offset:18432
	ds_read_b128 v[210:213], v163 offset:19456
	ds_read_b128 v[214:217], v163 offset:20480
	ds_read_b128 v[226:229], v163 offset:21504
	ds_read_b128 v[230:233], v163 offset:22528
	ds_read_b128 v[234:237], v163 offset:23552
	s_mov_b32 m0, s55
	s_nop 0
	global_load_lds_dwordx4 v158, s[40:41]
	s_mov_b32 m0, s56
	s_nop 0
	global_load_lds_dwordx4 v160, s[40:41]
	s_add_u32 s34, s40, 0x80000
	s_addc_u32 s35, s41, 0
	s_mov_b32 m0, s57
	s_nop 0
	global_load_lds_dwordx4 v158, s[34:35]
	s_mov_b32 m0, s58
	s_nop 0
	global_load_lds_dwordx4 v160, s[34:35]
	s_mov_b32 m0, s54
	s_nop 0
	global_load_lds_dwordx4 v149, s[42:43]
	s_mov_b32 m0, s59
	s_nop 0
	global_load_lds_dwordx4 v159, s[42:43]
	s_waitcnt vmcnt(8)
	s_waitcnt lgkmcnt(0)
	s_barrier
	s_setprio 1
	s_waitcnt lgkmcnt(7)
	v_mfma_f32_16x16x32_bf16 v[64:67], v[150:153], v[188:191], v[64:67]
	v_mfma_f32_16x16x32_bf16 v[60:63], v[164:167], v[188:191], v[60:63]
	s_waitcnt lgkmcnt(5)
	v_mfma_f32_16x16x32_bf16 v[48:51], v[150:153], v[206:209], v[48:51]
	v_mfma_f32_16x16x32_bf16 v[44:47], v[164:167], v[206:209], v[44:47]
	s_waitcnt lgkmcnt(3)
	v_mfma_f32_16x16x32_bf16 v[32:35], v[150:153], v[214:217], v[32:35]
	v_mfma_f32_16x16x32_bf16 v[28:31], v[164:167], v[214:217], v[28:31]
	s_waitcnt lgkmcnt(1)
	v_mfma_f32_16x16x32_bf16 v[16:19], v[150:153], v[230:233], v[16:19]
	v_mfma_f32_16x16x32_bf16 v[12:15], v[164:167], v[230:233], v[12:15]
	v_mfma_f32_16x16x32_bf16 v[64:67], v[154:157], v[192:195], v[64:67]
	v_mfma_f32_16x16x32_bf16 v[60:63], v[168:171], v[192:195], v[60:63]
	v_mfma_f32_16x16x32_bf16 v[48:51], v[154:157], v[210:213], v[48:51]
	v_mfma_f32_16x16x32_bf16 v[44:47], v[168:171], v[210:213], v[44:47]
	v_mfma_f32_16x16x32_bf16 v[32:35], v[154:157], v[226:229], v[32:35]
	v_mfma_f32_16x16x32_bf16 v[28:31], v[168:171], v[226:229], v[28:31]
	s_waitcnt lgkmcnt(0)
	v_mfma_f32_16x16x32_bf16 v[16:19], v[154:157], v[234:237], v[16:19]
	v_mfma_f32_16x16x32_bf16 v[12:15], v[168:171], v[234:237], v[12:15]
	s_setprio 0
	s_setprio 1
	v_mfma_f32_16x16x32_bf16 v[56:59], v[172:175], v[188:191], v[56:59]
	v_mfma_f32_16x16x32_bf16 v[52:55], v[180:183], v[188:191], v[52:55]
	v_mfma_f32_16x16x32_bf16 v[40:43], v[172:175], v[206:209], v[40:43]
	v_mfma_f32_16x16x32_bf16 v[36:39], v[180:183], v[206:209], v[36:39]
	v_mfma_f32_16x16x32_bf16 v[24:27], v[172:175], v[214:217], v[24:27]
	v_mfma_f32_16x16x32_bf16 v[20:23], v[180:183], v[214:217], v[20:23]
	v_mfma_f32_16x16x32_bf16 v[8:11], v[172:175], v[230:233], v[8:11]
	v_mfma_f32_16x16x32_bf16 v[4:7], v[180:183], v[230:233], v[4:7]
	v_mfma_f32_16x16x32_bf16 v[56:59], v[176:179], v[192:195], v[56:59]
	v_mfma_f32_16x16x32_bf16 v[52:55], v[184:187], v[192:195], v[52:55]
	v_mfma_f32_16x16x32_bf16 v[40:43], v[176:179], v[210:213], v[40:43]
	v_mfma_f32_16x16x32_bf16 v[36:39], v[184:187], v[210:213], v[36:39]
	v_mfma_f32_16x16x32_bf16 v[24:27], v[176:179], v[226:229], v[24:27]
	v_mfma_f32_16x16x32_bf16 v[20:23], v[184:187], v[226:229], v[20:23]
	v_mfma_f32_16x16x32_bf16 v[8:11], v[176:179], v[234:237], v[8:11]
	v_mfma_f32_16x16x32_bf16 v[4:7], v[184:187], v[234:237], v[4:7]
	s_setprio 0
	s_barrier
	v_add_u32_e32 v168, 0x18000, v162
	v_add_u32_e32 v184, 0x1c000, v162
	ds_read_b128 v[150:153], v168
	ds_read_b128 v[154:157], v168 offset:1024
	ds_read_b128 v[164:167], v168 offset:2048
	ds_read_b128 v[168:171], v168 offset:3072
	ds_read_b128 v[172:175], v184
	ds_read_b128 v[176:179], v184 offset:1024
	ds_read_b128 v[180:183], v184 offset:2048
	ds_read_b128 v[184:187], v184 offset:3072
	ds_read_b128 v[188:191], v163 offset:32768
	ds_read_b128 v[192:195], v163 offset:33792
	ds_read_b128 v[206:209], v163 offset:34816
	ds_read_b128 v[210:213], v163 offset:35840
	ds_read_b128 v[214:217], v163 offset:36864
	ds_read_b128 v[226:229], v163 offset:37888
	ds_read_b128 v[230:233], v163 offset:38912
	ds_read_b128 v[234:237], v163 offset:39936
	s_add_u32 s34, s42, 0x80000
	s_addc_u32 s35, s43, 0
	s_mov_b32 m0, s60
	s_nop 0
	global_load_lds_dwordx4 v149, s[34:35]
	s_mov_b32 m0, s61
	s_nop 0
	global_load_lds_dwordx4 v159, s[34:35]
	s_waitcnt vmcnt(8)
	s_waitcnt lgkmcnt(0)
	s_barrier
	s_setprio 1
	s_waitcnt lgkmcnt(7)
	v_mfma_f32_16x16x32_bf16 v[128:131], v[150:153], v[188:191], v[128:131]
	v_mfma_f32_16x16x32_bf16 v[124:127], v[164:167], v[188:191], v[124:127]
	s_waitcnt lgkmcnt(5)
	v_mfma_f32_16x16x32_bf16 v[112:115], v[150:153], v[206:209], v[112:115]
	v_mfma_f32_16x16x32_bf16 v[108:111], v[164:167], v[206:209], v[108:111]
	s_waitcnt lgkmcnt(3)
	v_mfma_f32_16x16x32_bf16 v[96:99], v[150:153], v[214:217], v[96:99]
	v_mfma_f32_16x16x32_bf16 v[92:95], v[164:167], v[214:217], v[92:95]
	s_waitcnt lgkmcnt(1)
	v_mfma_f32_16x16x32_bf16 v[80:83], v[150:153], v[230:233], v[80:83]
	v_mfma_f32_16x16x32_bf16 v[76:79], v[164:167], v[230:233], v[76:79]
	v_mfma_f32_16x16x32_bf16 v[128:131], v[154:157], v[192:195], v[128:131]
	v_mfma_f32_16x16x32_bf16 v[124:127], v[168:171], v[192:195], v[124:127]
	v_mfma_f32_16x16x32_bf16 v[112:115], v[154:157], v[210:213], v[112:115]
	v_mfma_f32_16x16x32_bf16 v[108:111], v[168:171], v[210:213], v[108:111]
	v_mfma_f32_16x16x32_bf16 v[96:99], v[154:157], v[226:229], v[96:99]
	v_mfma_f32_16x16x32_bf16 v[92:95], v[168:171], v[226:229], v[92:95]
	s_waitcnt lgkmcnt(0)
	v_mfma_f32_16x16x32_bf16 v[80:83], v[154:157], v[234:237], v[80:83]
	v_mfma_f32_16x16x32_bf16 v[76:79], v[168:171], v[234:237], v[76:79]
	s_setprio 0
	s_setprio 1
	v_mfma_f32_16x16x32_bf16 v[120:123], v[172:175], v[188:191], v[120:123]
	v_mfma_f32_16x16x32_bf16 v[116:119], v[180:183], v[188:191], v[116:119]
	v_mfma_f32_16x16x32_bf16 v[104:107], v[172:175], v[206:209], v[104:107]
	v_mfma_f32_16x16x32_bf16 v[100:103], v[180:183], v[206:209], v[100:103]
	v_mfma_f32_16x16x32_bf16 v[88:91], v[172:175], v[214:217], v[88:91]
	v_mfma_f32_16x16x32_bf16 v[84:87], v[180:183], v[214:217], v[84:87]
	v_mfma_f32_16x16x32_bf16 v[72:75], v[172:175], v[230:233], v[72:75]
	v_mfma_f32_16x16x32_bf16 v[68:71], v[180:183], v[230:233], v[68:71]
	v_mfma_f32_16x16x32_bf16 v[120:123], v[176:179], v[192:195], v[120:123]
	v_mfma_f32_16x16x32_bf16 v[116:119], v[184:187], v[192:195], v[116:119]
	v_mfma_f32_16x16x32_bf16 v[104:107], v[176:179], v[210:213], v[104:107]
	v_mfma_f32_16x16x32_bf16 v[100:103], v[184:187], v[210:213], v[100:103]
	v_mfma_f32_16x16x32_bf16 v[88:91], v[176:179], v[226:229], v[88:91]
	v_mfma_f32_16x16x32_bf16 v[84:87], v[184:187], v[226:229], v[84:87]
	v_mfma_f32_16x16x32_bf16 v[72:75], v[176:179], v[234:237], v[72:75]
	v_mfma_f32_16x16x32_bf16 v[68:71], v[184:187], v[234:237], v[68:71]
	s_setprio 0
	s_barrier
	ds_read_b128 v[188:191], v163 offset:49152
	ds_read_b128 v[192:195], v163 offset:50176
	ds_read_b128 v[206:209], v163 offset:51200
	ds_read_b128 v[210:213], v163 offset:52224
	ds_read_b128 v[214:217], v163 offset:53248
	ds_read_b128 v[226:229], v163 offset:54272
	ds_read_b128 v[230:233], v163 offset:55296
	ds_read_b128 v[234:237], v163 offset:56320
	s_add_u32 s34, s40, 0x80
	s_addc_u32 s35, s41, 0
	s_mov_b32 m0, s66
	s_nop 0
	global_load_lds_dwordx4 v158, s[34:35]
	s_mov_b32 m0, s67
	s_nop 0
	global_load_lds_dwordx4 v160, s[34:35]
	s_add_u32 s34, s40, 0x80080
	s_addc_u32 s35, s41, 0
	s_mov_b32 m0, s70
	s_nop 0
	global_load_lds_dwordx4 v158, s[34:35]
	s_mov_b32 m0, s71
	s_nop 0
	global_load_lds_dwordx4 v160, s[34:35]
	s_mov_b32 m0, s68
	s_nop 0
	global_load_lds_dwordx4 v149, s[2:3]
	s_mov_b32 m0, s69
	s_nop 0
	global_load_lds_dwordx4 v159, s[2:3]
	s_waitcnt vmcnt(8)
	s_waitcnt lgkmcnt(0)
	s_barrier
	s_setprio 1
	s_waitcnt lgkmcnt(7)
	v_mfma_f32_16x16x32_bf16 v[64:67], v[150:153], v[188:191], v[64:67]
	v_mfma_f32_16x16x32_bf16 v[60:63], v[164:167], v[188:191], v[60:63]
	s_add_u32 s14, s14, 0x100
	s_waitcnt lgkmcnt(5)
	v_mfma_f32_16x16x32_bf16 v[48:51], v[150:153], v[206:209], v[48:51]
	s_addc_u32 s15, s15, 0
	v_mfma_f32_16x16x32_bf16 v[44:47], v[164:167], v[206:209], v[44:47]
	s_add_u32 s25, s25, 0x100
	s_waitcnt lgkmcnt(3)
	v_mfma_f32_16x16x32_bf16 v[32:35], v[150:153], v[214:217], v[32:35]
	s_addc_u32 s27, s27, 0
	v_mfma_f32_16x16x32_bf16 v[28:31], v[164:167], v[214:217], v[28:31]
	s_mov_b32 s2, s33
	s_waitcnt lgkmcnt(1)
	v_mfma_f32_16x16x32_bf16 v[16:19], v[150:153], v[230:233], v[16:19]
	s_cmp_ge_i32 s33, s65
	v_mfma_f32_16x16x32_bf16 v[12:15], v[164:167], v[230:233], v[12:15]
	v_mfma_f32_16x16x32_bf16 v[64:67], v[154:157], v[192:195], v[64:67]
	v_mfma_f32_16x16x32_bf16 v[60:63], v[168:171], v[192:195], v[60:63]
	v_mfma_f32_16x16x32_bf16 v[48:51], v[154:157], v[210:213], v[48:51]
	v_mfma_f32_16x16x32_bf16 v[44:47], v[168:171], v[210:213], v[44:47]
	v_mfma_f32_16x16x32_bf16 v[32:35], v[154:157], v[226:229], v[32:35]
	v_mfma_f32_16x16x32_bf16 v[28:31], v[168:171], v[226:229], v[28:31]
	s_waitcnt lgkmcnt(0)
	v_mfma_f32_16x16x32_bf16 v[16:19], v[154:157], v[234:237], v[16:19]
	v_mfma_f32_16x16x32_bf16 v[12:15], v[168:171], v[234:237], v[12:15]
	s_setprio 0
	s_setprio 1
	v_mfma_f32_16x16x32_bf16 v[56:59], v[172:175], v[188:191], v[56:59]
	v_mfma_f32_16x16x32_bf16 v[52:55], v[180:183], v[188:191], v[52:55]
	v_mfma_f32_16x16x32_bf16 v[40:43], v[172:175], v[206:209], v[40:43]
	v_mfma_f32_16x16x32_bf16 v[36:39], v[180:183], v[206:209], v[36:39]
	v_mfma_f32_16x16x32_bf16 v[24:27], v[172:175], v[214:217], v[24:27]
	v_mfma_f32_16x16x32_bf16 v[20:23], v[180:183], v[214:217], v[20:23]
	v_mfma_f32_16x16x32_bf16 v[8:11], v[172:175], v[230:233], v[8:11]
	v_mfma_f32_16x16x32_bf16 v[4:7], v[180:183], v[230:233], v[4:7]
	v_mfma_f32_16x16x32_bf16 v[56:59], v[176:179], v[192:195], v[56:59]
	v_mfma_f32_16x16x32_bf16 v[52:55], v[184:187], v[192:195], v[52:55]
	v_mfma_f32_16x16x32_bf16 v[40:43], v[176:179], v[210:213], v[40:43]
	v_mfma_f32_16x16x32_bf16 v[36:39], v[184:187], v[210:213], v[36:39]
	v_mfma_f32_16x16x32_bf16 v[24:27], v[176:179], v[226:229], v[24:27]
	v_mfma_f32_16x16x32_bf16 v[20:23], v[184:187], v[226:229], v[20:23]
	v_mfma_f32_16x16x32_bf16 v[8:11], v[176:179], v[234:237], v[8:11]
	v_mfma_f32_16x16x32_bf16 v[4:7], v[184:187], v[234:237], v[4:7]
	s_setprio 0
	s_barrier
	s_cbranch_scc0 .LBB0_317

.LBB0_588:
	v_add_u32_e32 v150, 0x10000, v136
	v_add_u32_e32 v166, 0x14000, v136
	ds_read_b128 v[138:141], v150
	ds_read_b128 v[142:145], v150 offset:1024
	ds_read_b128 v[146:149], v150 offset:2048
	ds_read_b128 v[150:153], v150 offset:3072
	ds_read_b128 v[154:157], v166
	ds_read_b128 v[158:161], v166 offset:1024
	ds_read_b128 v[162:165], v166 offset:2048
	ds_read_b128 v[166:169], v166 offset:3072
	s_add_i32 s79, s42, 2
	s_cmp_eq_u32 s69, s42
	s_cselect_b32 s50, s29, s75
	s_cselect_b32 s51, s27, s76
	s_cselect_b32 s48, s74, s77
	s_cselect_b32 s49, s73, s78
	s_add_u32 s42, s50, 0x80
	s_addc_u32 s43, s51, 0
	ds_read_b128 v[170:173], v137
	ds_read_b128 v[174:177], v137 offset:1024
	ds_read_b128 v[178:181], v137 offset:2048
	ds_read_b128 v[182:185], v137 offset:3072
	ds_read_b128 v[186:189], v137 offset:4096
	ds_read_b128 v[190:193], v137 offset:5120
	ds_read_b128 v[194:197], v137 offset:6144
	ds_read_b128 v[206:209], v137 offset:7168
	s_mov_b32 m0, s70
	s_nop 0
	global_load_lds_dwordx4 v1, s[40:41]
	s_mov_b32 m0, s71
	s_nop 0
	global_load_lds_dwordx4 v132, s[40:41]
	s_waitcnt vmcnt(8)
	s_waitcnt lgkmcnt(0)
	s_barrier
	s_setprio 1
	s_waitcnt lgkmcnt(7)
	v_mfma_f32_16x16x32_bf16 v[124:127], v[138:141], v[170:173], v[124:127]
	v_mfma_f32_16x16x32_bf16 v[128:131], v[146:149], v[170:173], v[128:131]
	s_waitcnt lgkmcnt(5)
	v_mfma_f32_16x16x32_bf16 v[112:115], v[138:141], v[178:181], v[112:115]
	v_mfma_f32_16x16x32_bf16 v[108:111], v[146:149], v[178:181], v[108:111]
	s_waitcnt lgkmcnt(3)
	v_mfma_f32_16x16x32_bf16 v[96:99], v[138:141], v[186:189], v[96:99]
	v_mfma_f32_16x16x32_bf16 v[92:95], v[146:149], v[186:189], v[92:95]
	s_waitcnt lgkmcnt(1)
	v_mfma_f32_16x16x32_bf16 v[80:83], v[138:141], v[194:197], v[80:83]
	v_mfma_f32_16x16x32_bf16 v[76:79], v[146:149], v[194:197], v[76:79]
	v_mfma_f32_16x16x32_bf16 v[124:127], v[142:145], v[174:177], v[124:127]
	v_mfma_f32_16x16x32_bf16 v[128:131], v[150:153], v[174:177], v[128:131]
	v_mfma_f32_16x16x32_bf16 v[112:115], v[142:145], v[182:185], v[112:115]
	v_mfma_f32_16x16x32_bf16 v[108:111], v[150:153], v[182:185], v[108:111]
	v_mfma_f32_16x16x32_bf16 v[96:99], v[142:145], v[190:193], v[96:99]
	v_mfma_f32_16x16x32_bf16 v[92:95], v[150:153], v[190:193], v[92:95]
	s_waitcnt lgkmcnt(0)
	v_mfma_f32_16x16x32_bf16 v[80:83], v[142:145], v[206:209], v[80:83]
	v_mfma_f32_16x16x32_bf16 v[76:79], v[150:153], v[206:209], v[76:79]
	s_setprio 0
	s_setprio 1
	v_mfma_f32_16x16x32_bf16 v[120:123], v[154:157], v[170:173], v[120:123]
	v_mfma_f32_16x16x32_bf16 v[116:119], v[162:165], v[170:173], v[116:119]
	v_mfma_f32_16x16x32_bf16 v[104:107], v[154:157], v[178:181], v[104:107]
	v_mfma_f32_16x16x32_bf16 v[100:103], v[162:165], v[178:181], v[100:103]
	v_mfma_f32_16x16x32_bf16 v[88:91], v[154:157], v[186:189], v[88:91]
	v_mfma_f32_16x16x32_bf16 v[84:87], v[162:165], v[186:189], v[84:87]
	v_mfma_f32_16x16x32_bf16 v[72:75], v[154:157], v[194:197], v[72:75]
	v_mfma_f32_16x16x32_bf16 v[68:71], v[162:165], v[194:197], v[68:71]
	v_mfma_f32_16x16x32_bf16 v[120:123], v[158:161], v[174:177], v[120:123]
	v_mfma_f32_16x16x32_bf16 v[116:119], v[166:169], v[174:177], v[116:119]
	v_mfma_f32_16x16x32_bf16 v[104:107], v[158:161], v[182:185], v[104:107]
	v_mfma_f32_16x16x32_bf16 v[100:103], v[166:169], v[182:185], v[100:103]
	v_mfma_f32_16x16x32_bf16 v[88:91], v[158:161], v[190:193], v[88:91]
	v_mfma_f32_16x16x32_bf16 v[84:87], v[166:169], v[190:193], v[84:87]
	v_mfma_f32_16x16x32_bf16 v[72:75], v[158:161], v[206:209], v[72:75]
	v_mfma_f32_16x16x32_bf16 v[68:71], v[166:169], v[206:209], v[68:71]
	s_setprio 0
	s_barrier
	ds_read_b128 v[170:173], v137 offset:16384
	ds_read_b128 v[174:177], v137 offset:17408
	ds_read_b128 v[178:181], v137 offset:18432
	ds_read_b128 v[182:185], v137 offset:19456
	ds_read_b128 v[186:189], v137 offset:20480
	ds_read_b128 v[190:193], v137 offset:21504
	ds_read_b128 v[194:197], v137 offset:22528
	ds_read_b128 v[206:209], v137 offset:23552
	s_mov_b32 m0, s34
	s_nop 0
	global_load_lds_dwordx4 v2, s[48:49]
	s_mov_b32 m0, s35
	s_nop 0
	global_load_lds_dwordx4 v133, s[48:49]
	s_add_u32 s80, s48, 0x20000
	s_addc_u32 s81, s49, 0
	s_mov_b32 m0, s57
	s_nop 0
	global_load_lds_dwordx4 v2, s[80:81]
	s_mov_b32 m0, s58
	s_nop 0
	global_load_lds_dwordx4 v133, s[80:81]
	s_mov_b32 m0, s33
	s_nop 0
	global_load_lds_dwordx4 v1, s[50:51]
	s_mov_b32 m0, s59
	s_nop 0
	global_load_lds_dwordx4 v132, s[50:51]
	s_waitcnt vmcnt(8)
	s_waitcnt lgkmcnt(0)
	s_barrier
	s_setprio 1
	s_waitcnt lgkmcnt(7)
	v_mfma_f32_16x16x32_bf16 v[64:67], v[138:141], v[170:173], v[64:67]
	v_mfma_f32_16x16x32_bf16 v[60:63], v[146:149], v[170:173], v[60:63]
	s_waitcnt lgkmcnt(5)
	v_mfma_f32_16x16x32_bf16 v[48:51], v[138:141], v[178:181], v[48:51]
	v_mfma_f32_16x16x32_bf16 v[44:47], v[146:149], v[178:181], v[44:47]
	s_waitcnt lgkmcnt(3)
	v_mfma_f32_16x16x32_bf16 v[32:35], v[138:141], v[186:189], v[32:35]
	v_mfma_f32_16x16x32_bf16 v[28:31], v[146:149], v[186:189], v[28:31]
	s_waitcnt lgkmcnt(1)
	v_mfma_f32_16x16x32_bf16 v[16:19], v[138:141], v[194:197], v[16:19]
	v_mfma_f32_16x16x32_bf16 v[12:15], v[146:149], v[194:197], v[12:15]
	v_mfma_f32_16x16x32_bf16 v[64:67], v[142:145], v[174:177], v[64:67]
	v_mfma_f32_16x16x32_bf16 v[60:63], v[150:153], v[174:177], v[60:63]
	v_mfma_f32_16x16x32_bf16 v[48:51], v[142:145], v[182:185], v[48:51]
	v_mfma_f32_16x16x32_bf16 v[44:47], v[150:153], v[182:185], v[44:47]
	v_mfma_f32_16x16x32_bf16 v[32:35], v[142:145], v[190:193], v[32:35]
	v_mfma_f32_16x16x32_bf16 v[28:31], v[150:153], v[190:193], v[28:31]
	s_waitcnt lgkmcnt(0)
	v_mfma_f32_16x16x32_bf16 v[16:19], v[142:145], v[206:209], v[16:19]
	v_mfma_f32_16x16x32_bf16 v[12:15], v[150:153], v[206:209], v[12:15]
	s_setprio 0
	s_setprio 1
	v_mfma_f32_16x16x32_bf16 v[56:59], v[154:157], v[170:173], v[56:59]
	v_mfma_f32_16x16x32_bf16 v[52:55], v[162:165], v[170:173], v[52:55]
	v_mfma_f32_16x16x32_bf16 v[40:43], v[154:157], v[178:181], v[40:43]
	v_mfma_f32_16x16x32_bf16 v[36:39], v[162:165], v[178:181], v[36:39]
	v_mfma_f32_16x16x32_bf16 v[24:27], v[154:157], v[186:189], v[24:27]
	v_mfma_f32_16x16x32_bf16 v[20:23], v[162:165], v[186:189], v[20:23]
	v_mfma_f32_16x16x32_bf16 v[8:11], v[154:157], v[194:197], v[8:11]
	v_mfma_f32_16x16x32_bf16 v[4:7], v[162:165], v[194:197], v[4:7]
	v_mfma_f32_16x16x32_bf16 v[56:59], v[158:161], v[174:177], v[56:59]
	v_mfma_f32_16x16x32_bf16 v[52:55], v[166:169], v[174:177], v[52:55]
	v_mfma_f32_16x16x32_bf16 v[40:43], v[158:161], v[182:185], v[40:43]
	v_mfma_f32_16x16x32_bf16 v[36:39], v[166:169], v[182:185], v[36:39]
	v_mfma_f32_16x16x32_bf16 v[24:27], v[158:161], v[190:193], v[24:27]
	v_mfma_f32_16x16x32_bf16 v[20:23], v[166:169], v[190:193], v[20:23]
	v_mfma_f32_16x16x32_bf16 v[8:11], v[158:161], v[206:209], v[8:11]
	v_mfma_f32_16x16x32_bf16 v[4:7], v[166:169], v[206:209], v[4:7]
	s_setprio 0
	s_barrier
	v_add_u32_e32 v150, 0x18000, v136
	v_add_u32_e32 v166, 0x1c000, v136
	ds_read_b128 v[138:141], v150
	ds_read_b128 v[142:145], v150 offset:1024
	ds_read_b128 v[146:149], v150 offset:2048
	ds_read_b128 v[150:153], v150 offset:3072
	ds_read_b128 v[154:157], v166
	ds_read_b128 v[158:161], v166 offset:1024
	ds_read_b128 v[162:165], v166 offset:2048
	ds_read_b128 v[166:169], v166 offset:3072
	ds_read_b128 v[170:173], v137 offset:32768
	ds_read_b128 v[174:177], v137 offset:33792
	ds_read_b128 v[178:181], v137 offset:34816
	ds_read_b128 v[182:185], v137 offset:35840
	ds_read_b128 v[186:189], v137 offset:36864
	ds_read_b128 v[190:193], v137 offset:37888
	ds_read_b128 v[194:197], v137 offset:38912
	ds_read_b128 v[206:209], v137 offset:39936
	s_add_u32 s50, s50, 0x20000
	s_addc_u32 s51, s51, 0
	s_mov_b32 m0, s60
	s_nop 0
	global_load_lds_dwordx4 v1, s[50:51]
	s_mov_b32 m0, s61
	s_nop 0
	global_load_lds_dwordx4 v132, s[50:51]
	s_waitcnt vmcnt(8)
	s_waitcnt lgkmcnt(0)
	s_barrier
	s_setprio 1
	s_waitcnt lgkmcnt(7)
	v_mfma_f32_16x16x32_bf16 v[124:127], v[138:141], v[170:173], v[124:127]
	v_mfma_f32_16x16x32_bf16 v[128:131], v[146:149], v[170:173], v[128:131]
	s_waitcnt lgkmcnt(5)
	v_mfma_f32_16x16x32_bf16 v[112:115], v[138:141], v[178:181], v[112:115]
	v_mfma_f32_16x16x32_bf16 v[108:111], v[146:149], v[178:181], v[108:111]
	s_waitcnt lgkmcnt(3)
	v_mfma_f32_16x16x32_bf16 v[96:99], v[138:141], v[186:189], v[96:99]
	v_mfma_f32_16x16x32_bf16 v[92:95], v[146:149], v[186:189], v[92:95]
	s_waitcnt lgkmcnt(1)
	v_mfma_f32_16x16x32_bf16 v[80:83], v[138:141], v[194:197], v[80:83]
	v_mfma_f32_16x16x32_bf16 v[76:79], v[146:149], v[194:197], v[76:79]
	v_mfma_f32_16x16x32_bf16 v[124:127], v[142:145], v[174:177], v[124:127]
	v_mfma_f32_16x16x32_bf16 v[128:131], v[150:153], v[174:177], v[128:131]
	v_mfma_f32_16x16x32_bf16 v[112:115], v[142:145], v[182:185], v[112:115]
	v_mfma_f32_16x16x32_bf16 v[108:111], v[150:153], v[182:185], v[108:111]
	v_mfma_f32_16x16x32_bf16 v[96:99], v[142:145], v[190:193], v[96:99]
	v_mfma_f32_16x16x32_bf16 v[92:95], v[150:153], v[190:193], v[92:95]
	s_waitcnt lgkmcnt(0)
	v_mfma_f32_16x16x32_bf16 v[80:83], v[142:145], v[206:209], v[80:83]
	v_mfma_f32_16x16x32_bf16 v[76:79], v[150:153], v[206:209], v[76:79]
	s_setprio 0
	s_setprio 1
	v_mfma_f32_16x16x32_bf16 v[120:123], v[154:157], v[170:173], v[120:123]
	v_mfma_f32_16x16x32_bf16 v[116:119], v[162:165], v[170:173], v[116:119]
	v_mfma_f32_16x16x32_bf16 v[104:107], v[154:157], v[178:181], v[104:107]
	v_mfma_f32_16x16x32_bf16 v[100:103], v[162:165], v[178:181], v[100:103]
	v_mfma_f32_16x16x32_bf16 v[88:91], v[154:157], v[186:189], v[88:91]
	v_mfma_f32_16x16x32_bf16 v[84:87], v[162:165], v[186:189], v[84:87]
	v_mfma_f32_16x16x32_bf16 v[72:75], v[154:157], v[194:197], v[72:75]
	v_mfma_f32_16x16x32_bf16 v[68:71], v[162:165], v[194:197], v[68:71]
	v_mfma_f32_16x16x32_bf16 v[120:123], v[158:161], v[174:177], v[120:123]
	v_mfma_f32_16x16x32_bf16 v[116:119], v[166:169], v[174:177], v[116:119]
	v_mfma_f32_16x16x32_bf16 v[104:107], v[158:161], v[182:185], v[104:107]
	v_mfma_f32_16x16x32_bf16 v[100:103], v[166:169], v[182:185], v[100:103]
	v_mfma_f32_16x16x32_bf16 v[88:91], v[158:161], v[190:193], v[88:91]
	v_mfma_f32_16x16x32_bf16 v[84:87], v[166:169], v[190:193], v[84:87]
	v_mfma_f32_16x16x32_bf16 v[72:75], v[158:161], v[206:209], v[72:75]
	v_mfma_f32_16x16x32_bf16 v[68:71], v[166:169], v[206:209], v[68:71]
	s_setprio 0
	s_barrier
	ds_read_b128 v[170:173], v137 offset:49152
	ds_read_b128 v[174:177], v137 offset:50176
	ds_read_b128 v[178:181], v137 offset:51200
	ds_read_b128 v[182:185], v137 offset:52224
	ds_read_b128 v[186:189], v137 offset:53248
	ds_read_b128 v[190:193], v137 offset:54272
	ds_read_b128 v[194:197], v137 offset:55296
	ds_read_b128 v[206:209], v137 offset:56320
	s_add_u32 s50, s48, 0x80
	s_addc_u32 s51, s49, 0
	s_mov_b32 m0, s63
	s_nop 0
	global_load_lds_dwordx4 v2, s[50:51]
	s_add_u32 s48, s48, 0x20080
	s_mov_b32 m0, s64
	s_nop 0
	global_load_lds_dwordx4 v133, s[50:51]
	s_addc_u32 s49, s49, 0
	s_mov_b32 m0, s67
	s_nop 0
	global_load_lds_dwordx4 v2, s[48:49]
	s_mov_b32 m0, s68
	s_nop 0
	global_load_lds_dwordx4 v133, s[48:49]
	s_mov_b32 m0, s65
	s_nop 0
	global_load_lds_dwordx4 v1, s[42:43]
	s_mov_b32 m0, s66
	s_nop 0
	global_load_lds_dwordx4 v132, s[42:43]
	s_waitcnt vmcnt(8)
	s_waitcnt lgkmcnt(0)
	s_barrier
	s_setprio 1
	s_waitcnt lgkmcnt(7)
	v_mfma_f32_16x16x32_bf16 v[64:67], v[138:141], v[170:173], v[64:67]
	v_mfma_f32_16x16x32_bf16 v[60:63], v[146:149], v[170:173], v[60:63]
	s_add_u32 s75, s75, 0x100
	s_waitcnt lgkmcnt(5)
	v_mfma_f32_16x16x32_bf16 v[48:51], v[138:141], v[178:181], v[48:51]
	s_addc_u32 s76, s76, 0
	v_mfma_f32_16x16x32_bf16 v[44:47], v[146:149], v[178:181], v[44:47]
	s_add_u32 s77, s77, 0x100
	s_waitcnt lgkmcnt(3)
	v_mfma_f32_16x16x32_bf16 v[32:35], v[138:141], v[186:189], v[32:35]
	s_addc_u32 s78, s78, 0
	v_mfma_f32_16x16x32_bf16 v[28:31], v[146:149], v[186:189], v[28:31]
	s_add_u32 s40, s40, 0x100
	s_waitcnt lgkmcnt(1)
	v_mfma_f32_16x16x32_bf16 v[16:19], v[138:141], v[194:197], v[16:19]
	s_addc_u32 s41, s41, 0
	v_mfma_f32_16x16x32_bf16 v[12:15], v[146:149], v[194:197], v[12:15]
	s_mov_b32 s42, s79
	v_mfma_f32_16x16x32_bf16 v[64:67], v[142:145], v[174:177], v[64:67]
	s_cmp_ge_i32 s79, s62
	v_mfma_f32_16x16x32_bf16 v[60:63], v[150:153], v[174:177], v[60:63]
	v_mfma_f32_16x16x32_bf16 v[48:51], v[142:145], v[182:185], v[48:51]
	v_mfma_f32_16x16x32_bf16 v[44:47], v[150:153], v[182:185], v[44:47]
	v_mfma_f32_16x16x32_bf16 v[32:35], v[142:145], v[190:193], v[32:35]
	v_mfma_f32_16x16x32_bf16 v[28:31], v[150:153], v[190:193], v[28:31]
	s_waitcnt lgkmcnt(0)
	v_mfma_f32_16x16x32_bf16 v[16:19], v[142:145], v[206:209], v[16:19]
	v_mfma_f32_16x16x32_bf16 v[12:15], v[150:153], v[206:209], v[12:15]
	s_setprio 0
	s_setprio 1
	v_mfma_f32_16x16x32_bf16 v[56:59], v[154:157], v[170:173], v[56:59]
	v_mfma_f32_16x16x32_bf16 v[52:55], v[162:165], v[170:173], v[52:55]
	v_mfma_f32_16x16x32_bf16 v[40:43], v[154:157], v[178:181], v[40:43]
	v_mfma_f32_16x16x32_bf16 v[36:39], v[162:165], v[178:181], v[36:39]
	v_mfma_f32_16x16x32_bf16 v[24:27], v[154:157], v[186:189], v[24:27]
	v_mfma_f32_16x16x32_bf16 v[20:23], v[162:165], v[186:189], v[20:23]
	v_mfma_f32_16x16x32_bf16 v[8:11], v[154:157], v[194:197], v[8:11]
	v_mfma_f32_16x16x32_bf16 v[4:7], v[162:165], v[194:197], v[4:7]
	v_mfma_f32_16x16x32_bf16 v[56:59], v[158:161], v[174:177], v[56:59]
	v_mfma_f32_16x16x32_bf16 v[52:55], v[166:169], v[174:177], v[52:55]
	v_mfma_f32_16x16x32_bf16 v[40:43], v[158:161], v[182:185], v[40:43]
	v_mfma_f32_16x16x32_bf16 v[36:39], v[166:169], v[182:185], v[36:39]
	v_mfma_f32_16x16x32_bf16 v[24:27], v[158:161], v[190:193], v[24:27]
	v_mfma_f32_16x16x32_bf16 v[20:23], v[166:169], v[190:193], v[20:23]
	v_mfma_f32_16x16x32_bf16 v[8:11], v[158:161], v[206:209], v[8:11]
	v_mfma_f32_16x16x32_bf16 v[4:7], v[166:169], v[206:209], v[4:7]
	s_setprio 0
	s_barrier
	s_cbranch_scc0 .LBB0_588

.LBB0_605:
	v_add_u32_e32 v150, 0x10000, v136
	v_add_u32_e32 v166, 0x14000, v136
	ds_read_b128 v[138:141], v150
	ds_read_b128 v[142:145], v150 offset:1024
	ds_read_b128 v[146:149], v150 offset:2048
	ds_read_b128 v[150:153], v150 offset:3072
	ds_read_b128 v[154:157], v166
	ds_read_b128 v[158:161], v166 offset:1024
	ds_read_b128 v[162:165], v166 offset:2048
	ds_read_b128 v[166:169], v166 offset:3072
	s_add_i32 s79, s42, 2
	s_cmp_eq_u32 s68, s42
	s_cselect_b32 s50, s27, s75
	s_cselect_b32 s51, s3, s76
	s_cselect_b32 s48, s74, s77
	s_cselect_b32 s49, s73, s78
	s_add_u32 s42, s50, 0x80
	s_addc_u32 s43, s51, 0
	ds_read_b128 v[170:173], v137
	ds_read_b128 v[174:177], v137 offset:1024
	ds_read_b128 v[178:181], v137 offset:2048
	ds_read_b128 v[182:185], v137 offset:3072
	ds_read_b128 v[186:189], v137 offset:4096
	ds_read_b128 v[190:193], v137 offset:5120
	ds_read_b128 v[194:197], v137 offset:6144
	ds_read_b128 v[206:209], v137 offset:7168
	s_mov_b32 m0, s69
	s_nop 0
	global_load_lds_dwordx4 v1, s[40:41]
	s_mov_b32 m0, s70
	s_nop 0
	global_load_lds_dwordx4 v132, s[40:41]
	s_waitcnt vmcnt(8)
	s_waitcnt lgkmcnt(0)
	s_barrier
	s_setprio 1
	s_waitcnt lgkmcnt(7)
	v_mfma_f32_16x16x32_bf16 v[124:127], v[138:141], v[170:173], v[124:127]
	v_mfma_f32_16x16x32_bf16 v[128:131], v[146:149], v[170:173], v[128:131]
	s_waitcnt lgkmcnt(5)
	v_mfma_f32_16x16x32_bf16 v[112:115], v[138:141], v[178:181], v[112:115]
	v_mfma_f32_16x16x32_bf16 v[108:111], v[146:149], v[178:181], v[108:111]
	s_waitcnt lgkmcnt(3)
	v_mfma_f32_16x16x32_bf16 v[96:99], v[138:141], v[186:189], v[96:99]
	v_mfma_f32_16x16x32_bf16 v[92:95], v[146:149], v[186:189], v[92:95]
	s_waitcnt lgkmcnt(1)
	v_mfma_f32_16x16x32_bf16 v[80:83], v[138:141], v[194:197], v[80:83]
	v_mfma_f32_16x16x32_bf16 v[76:79], v[146:149], v[194:197], v[76:79]
	v_mfma_f32_16x16x32_bf16 v[124:127], v[142:145], v[174:177], v[124:127]
	v_mfma_f32_16x16x32_bf16 v[128:131], v[150:153], v[174:177], v[128:131]
	v_mfma_f32_16x16x32_bf16 v[112:115], v[142:145], v[182:185], v[112:115]
	v_mfma_f32_16x16x32_bf16 v[108:111], v[150:153], v[182:185], v[108:111]
	v_mfma_f32_16x16x32_bf16 v[96:99], v[142:145], v[190:193], v[96:99]
	v_mfma_f32_16x16x32_bf16 v[92:95], v[150:153], v[190:193], v[92:95]
	s_waitcnt lgkmcnt(0)
	v_mfma_f32_16x16x32_bf16 v[80:83], v[142:145], v[206:209], v[80:83]
	v_mfma_f32_16x16x32_bf16 v[76:79], v[150:153], v[206:209], v[76:79]
	s_setprio 0
	s_setprio 1
	v_mfma_f32_16x16x32_bf16 v[120:123], v[154:157], v[170:173], v[120:123]
	v_mfma_f32_16x16x32_bf16 v[116:119], v[162:165], v[170:173], v[116:119]
	v_mfma_f32_16x16x32_bf16 v[104:107], v[154:157], v[178:181], v[104:107]
	v_mfma_f32_16x16x32_bf16 v[100:103], v[162:165], v[178:181], v[100:103]
	v_mfma_f32_16x16x32_bf16 v[88:91], v[154:157], v[186:189], v[88:91]
	v_mfma_f32_16x16x32_bf16 v[84:87], v[162:165], v[186:189], v[84:87]
	v_mfma_f32_16x16x32_bf16 v[72:75], v[154:157], v[194:197], v[72:75]
	v_mfma_f32_16x16x32_bf16 v[68:71], v[162:165], v[194:197], v[68:71]
	v_mfma_f32_16x16x32_bf16 v[120:123], v[158:161], v[174:177], v[120:123]
	v_mfma_f32_16x16x32_bf16 v[116:119], v[166:169], v[174:177], v[116:119]
	v_mfma_f32_16x16x32_bf16 v[104:107], v[158:161], v[182:185], v[104:107]
	v_mfma_f32_16x16x32_bf16 v[100:103], v[166:169], v[182:185], v[100:103]
	v_mfma_f32_16x16x32_bf16 v[88:91], v[158:161], v[190:193], v[88:91]
	v_mfma_f32_16x16x32_bf16 v[84:87], v[166:169], v[190:193], v[84:87]
	v_mfma_f32_16x16x32_bf16 v[72:75], v[158:161], v[206:209], v[72:75]
	v_mfma_f32_16x16x32_bf16 v[68:71], v[166:169], v[206:209], v[68:71]
	s_setprio 0
	s_barrier
	ds_read_b128 v[170:173], v137 offset:16384
	ds_read_b128 v[174:177], v137 offset:17408
	ds_read_b128 v[178:181], v137 offset:18432
	ds_read_b128 v[182:185], v137 offset:19456
	ds_read_b128 v[186:189], v137 offset:20480
	ds_read_b128 v[190:193], v137 offset:21504
	ds_read_b128 v[194:197], v137 offset:22528
	ds_read_b128 v[206:209], v137 offset:23552
	s_mov_b32 m0, s29
	s_nop 0
	global_load_lds_dwordx4 v2, s[48:49]
	s_mov_b32 m0, s34
	s_nop 0
	global_load_lds_dwordx4 v133, s[48:49]
	s_add_u32 s80, s48, 0x10000
	s_addc_u32 s81, s49, 0
	s_mov_b32 m0, s35
	s_nop 0
	global_load_lds_dwordx4 v2, s[80:81]
	s_mov_b32 m0, s57
	s_nop 0
	global_load_lds_dwordx4 v133, s[80:81]
	s_mov_b32 m0, s0
	s_nop 0
	global_load_lds_dwordx4 v1, s[50:51]
	s_mov_b32 m0, s58
	s_nop 0
	global_load_lds_dwordx4 v132, s[50:51]
	s_waitcnt vmcnt(8)
	s_waitcnt lgkmcnt(0)
	s_barrier
	s_setprio 1
	s_waitcnt lgkmcnt(7)
	v_mfma_f32_16x16x32_bf16 v[64:67], v[138:141], v[170:173], v[64:67]
	v_mfma_f32_16x16x32_bf16 v[60:63], v[146:149], v[170:173], v[60:63]
	s_waitcnt lgkmcnt(5)
	v_mfma_f32_16x16x32_bf16 v[48:51], v[138:141], v[178:181], v[48:51]
	v_mfma_f32_16x16x32_bf16 v[44:47], v[146:149], v[178:181], v[44:47]
	s_waitcnt lgkmcnt(3)
	v_mfma_f32_16x16x32_bf16 v[32:35], v[138:141], v[186:189], v[32:35]
	v_mfma_f32_16x16x32_bf16 v[28:31], v[146:149], v[186:189], v[28:31]
	s_waitcnt lgkmcnt(1)
	v_mfma_f32_16x16x32_bf16 v[16:19], v[138:141], v[194:197], v[16:19]
	v_mfma_f32_16x16x32_bf16 v[12:15], v[146:149], v[194:197], v[12:15]
	v_mfma_f32_16x16x32_bf16 v[64:67], v[142:145], v[174:177], v[64:67]
	v_mfma_f32_16x16x32_bf16 v[60:63], v[150:153], v[174:177], v[60:63]
	v_mfma_f32_16x16x32_bf16 v[48:51], v[142:145], v[182:185], v[48:51]
	v_mfma_f32_16x16x32_bf16 v[44:47], v[150:153], v[182:185], v[44:47]
	v_mfma_f32_16x16x32_bf16 v[32:35], v[142:145], v[190:193], v[32:35]
	v_mfma_f32_16x16x32_bf16 v[28:31], v[150:153], v[190:193], v[28:31]
	s_waitcnt lgkmcnt(0)
	v_mfma_f32_16x16x32_bf16 v[16:19], v[142:145], v[206:209], v[16:19]
	v_mfma_f32_16x16x32_bf16 v[12:15], v[150:153], v[206:209], v[12:15]
	s_setprio 0
	s_setprio 1
	v_mfma_f32_16x16x32_bf16 v[56:59], v[154:157], v[170:173], v[56:59]
	v_mfma_f32_16x16x32_bf16 v[52:55], v[162:165], v[170:173], v[52:55]
	v_mfma_f32_16x16x32_bf16 v[40:43], v[154:157], v[178:181], v[40:43]
	v_mfma_f32_16x16x32_bf16 v[36:39], v[162:165], v[178:181], v[36:39]
	v_mfma_f32_16x16x32_bf16 v[24:27], v[154:157], v[186:189], v[24:27]
	v_mfma_f32_16x16x32_bf16 v[20:23], v[162:165], v[186:189], v[20:23]
	v_mfma_f32_16x16x32_bf16 v[8:11], v[154:157], v[194:197], v[8:11]
	v_mfma_f32_16x16x32_bf16 v[4:7], v[162:165], v[194:197], v[4:7]
	v_mfma_f32_16x16x32_bf16 v[56:59], v[158:161], v[174:177], v[56:59]
	v_mfma_f32_16x16x32_bf16 v[52:55], v[166:169], v[174:177], v[52:55]
	v_mfma_f32_16x16x32_bf16 v[40:43], v[158:161], v[182:185], v[40:43]
	v_mfma_f32_16x16x32_bf16 v[36:39], v[166:169], v[182:185], v[36:39]
	v_mfma_f32_16x16x32_bf16 v[24:27], v[158:161], v[190:193], v[24:27]
	v_mfma_f32_16x16x32_bf16 v[20:23], v[166:169], v[190:193], v[20:23]
	v_mfma_f32_16x16x32_bf16 v[8:11], v[158:161], v[206:209], v[8:11]
	v_mfma_f32_16x16x32_bf16 v[4:7], v[166:169], v[206:209], v[4:7]
	s_setprio 0
	s_barrier
	v_add_u32_e32 v150, 0x18000, v136
	v_add_u32_e32 v166, 0x1c000, v136
	ds_read_b128 v[138:141], v150
	ds_read_b128 v[142:145], v150 offset:1024
	ds_read_b128 v[146:149], v150 offset:2048
	ds_read_b128 v[150:153], v150 offset:3072
	ds_read_b128 v[154:157], v166
	ds_read_b128 v[158:161], v166 offset:1024
	ds_read_b128 v[162:165], v166 offset:2048
	ds_read_b128 v[166:169], v166 offset:3072
	ds_read_b128 v[170:173], v137 offset:32768
	ds_read_b128 v[174:177], v137 offset:33792
	ds_read_b128 v[178:181], v137 offset:34816
	ds_read_b128 v[182:185], v137 offset:35840
	ds_read_b128 v[186:189], v137 offset:36864
	ds_read_b128 v[190:193], v137 offset:37888
	ds_read_b128 v[194:197], v137 offset:38912
	ds_read_b128 v[206:209], v137 offset:39936
	s_add_u32 s50, s50, 0x10000
	s_addc_u32 s51, s51, 0
	s_mov_b32 m0, s59
	s_nop 0
	global_load_lds_dwordx4 v1, s[50:51]
	s_mov_b32 m0, s60
	s_nop 0
	global_load_lds_dwordx4 v132, s[50:51]
	s_waitcnt vmcnt(8)
	s_waitcnt lgkmcnt(0)
	s_barrier
	s_setprio 1
	s_waitcnt lgkmcnt(7)
	v_mfma_f32_16x16x32_bf16 v[124:127], v[138:141], v[170:173], v[124:127]
	v_mfma_f32_16x16x32_bf16 v[128:131], v[146:149], v[170:173], v[128:131]
	s_waitcnt lgkmcnt(5)
	v_mfma_f32_16x16x32_bf16 v[112:115], v[138:141], v[178:181], v[112:115]
	v_mfma_f32_16x16x32_bf16 v[108:111], v[146:149], v[178:181], v[108:111]
	s_waitcnt lgkmcnt(3)
	v_mfma_f32_16x16x32_bf16 v[96:99], v[138:141], v[186:189], v[96:99]
	v_mfma_f32_16x16x32_bf16 v[92:95], v[146:149], v[186:189], v[92:95]
	s_waitcnt lgkmcnt(1)
	v_mfma_f32_16x16x32_bf16 v[80:83], v[138:141], v[194:197], v[80:83]
	v_mfma_f32_16x16x32_bf16 v[76:79], v[146:149], v[194:197], v[76:79]
	v_mfma_f32_16x16x32_bf16 v[124:127], v[142:145], v[174:177], v[124:127]
	v_mfma_f32_16x16x32_bf16 v[128:131], v[150:153], v[174:177], v[128:131]
	v_mfma_f32_16x16x32_bf16 v[112:115], v[142:145], v[182:185], v[112:115]
	v_mfma_f32_16x16x32_bf16 v[108:111], v[150:153], v[182:185], v[108:111]
	v_mfma_f32_16x16x32_bf16 v[96:99], v[142:145], v[190:193], v[96:99]
	v_mfma_f32_16x16x32_bf16 v[92:95], v[150:153], v[190:193], v[92:95]
	s_waitcnt lgkmcnt(0)
	v_mfma_f32_16x16x32_bf16 v[80:83], v[142:145], v[206:209], v[80:83]
	v_mfma_f32_16x16x32_bf16 v[76:79], v[150:153], v[206:209], v[76:79]
	s_setprio 0
	s_setprio 1
	v_mfma_f32_16x16x32_bf16 v[120:123], v[154:157], v[170:173], v[120:123]
	v_mfma_f32_16x16x32_bf16 v[116:119], v[162:165], v[170:173], v[116:119]
	v_mfma_f32_16x16x32_bf16 v[104:107], v[154:157], v[178:181], v[104:107]
	v_mfma_f32_16x16x32_bf16 v[100:103], v[162:165], v[178:181], v[100:103]
	v_mfma_f32_16x16x32_bf16 v[88:91], v[154:157], v[186:189], v[88:91]
	v_mfma_f32_16x16x32_bf16 v[84:87], v[162:165], v[186:189], v[84:87]
	v_mfma_f32_16x16x32_bf16 v[72:75], v[154:157], v[194:197], v[72:75]
	v_mfma_f32_16x16x32_bf16 v[68:71], v[162:165], v[194:197], v[68:71]
	v_mfma_f32_16x16x32_bf16 v[120:123], v[158:161], v[174:177], v[120:123]
	v_mfma_f32_16x16x32_bf16 v[116:119], v[166:169], v[174:177], v[116:119]
	v_mfma_f32_16x16x32_bf16 v[104:107], v[158:161], v[182:185], v[104:107]
	v_mfma_f32_16x16x32_bf16 v[100:103], v[166:169], v[182:185], v[100:103]
	v_mfma_f32_16x16x32_bf16 v[88:91], v[158:161], v[190:193], v[88:91]
	v_mfma_f32_16x16x32_bf16 v[84:87], v[166:169], v[190:193], v[84:87]
	v_mfma_f32_16x16x32_bf16 v[72:75], v[158:161], v[206:209], v[72:75]
	v_mfma_f32_16x16x32_bf16 v[68:71], v[166:169], v[206:209], v[68:71]
	s_setprio 0
	s_barrier
	ds_read_b128 v[170:173], v137 offset:49152
	ds_read_b128 v[174:177], v137 offset:50176
	ds_read_b128 v[178:181], v137 offset:51200
	ds_read_b128 v[182:185], v137 offset:52224
	ds_read_b128 v[186:189], v137 offset:53248
	ds_read_b128 v[190:193], v137 offset:54272
	ds_read_b128 v[194:197], v137 offset:55296
	ds_read_b128 v[206:209], v137 offset:56320
	s_add_u32 s50, s48, 0x80
	s_addc_u32 s51, s49, 0
	s_mov_b32 m0, s62
	s_nop 0
	global_load_lds_dwordx4 v2, s[50:51]
	s_add_u32 s48, s48, 0x10080
	s_mov_b32 m0, s63
	s_nop 0
	global_load_lds_dwordx4 v133, s[50:51]
	s_addc_u32 s49, s49, 0
	s_mov_b32 m0, s66
	s_nop 0
	global_load_lds_dwordx4 v2, s[48:49]
	s_mov_b32 m0, s67
	s_nop 0
	global_load_lds_dwordx4 v133, s[48:49]
	s_mov_b32 m0, s64
	s_nop 0
	global_load_lds_dwordx4 v1, s[42:43]
	s_mov_b32 m0, s65
	s_nop 0
	global_load_lds_dwordx4 v132, s[42:43]
	s_waitcnt vmcnt(8)
	s_waitcnt lgkmcnt(0)
	s_barrier
	s_setprio 1
	s_waitcnt lgkmcnt(7)
	v_mfma_f32_16x16x32_bf16 v[64:67], v[138:141], v[170:173], v[64:67]
	v_mfma_f32_16x16x32_bf16 v[60:63], v[146:149], v[170:173], v[60:63]
	s_add_u32 s75, s75, 0x100
	s_waitcnt lgkmcnt(5)
	v_mfma_f32_16x16x32_bf16 v[48:51], v[138:141], v[178:181], v[48:51]
	s_addc_u32 s76, s76, 0
	v_mfma_f32_16x16x32_bf16 v[44:47], v[146:149], v[178:181], v[44:47]
	s_add_u32 s77, s77, 0x100
	s_waitcnt lgkmcnt(3)
	v_mfma_f32_16x16x32_bf16 v[32:35], v[138:141], v[186:189], v[32:35]
	s_addc_u32 s78, s78, 0
	v_mfma_f32_16x16x32_bf16 v[28:31], v[146:149], v[186:189], v[28:31]
	s_add_u32 s40, s40, 0x100
	s_waitcnt lgkmcnt(1)
	v_mfma_f32_16x16x32_bf16 v[16:19], v[138:141], v[194:197], v[16:19]
	s_addc_u32 s41, s41, 0
	v_mfma_f32_16x16x32_bf16 v[12:15], v[146:149], v[194:197], v[12:15]
	s_mov_b32 s42, s79
	v_mfma_f32_16x16x32_bf16 v[64:67], v[142:145], v[174:177], v[64:67]
	s_cmp_ge_i32 s79, s61
	v_mfma_f32_16x16x32_bf16 v[60:63], v[150:153], v[174:177], v[60:63]
	v_mfma_f32_16x16x32_bf16 v[48:51], v[142:145], v[182:185], v[48:51]
	v_mfma_f32_16x16x32_bf16 v[44:47], v[150:153], v[182:185], v[44:47]
	v_mfma_f32_16x16x32_bf16 v[32:35], v[142:145], v[190:193], v[32:35]
	v_mfma_f32_16x16x32_bf16 v[28:31], v[150:153], v[190:193], v[28:31]
	s_waitcnt lgkmcnt(0)
	v_mfma_f32_16x16x32_bf16 v[16:19], v[142:145], v[206:209], v[16:19]
	v_mfma_f32_16x16x32_bf16 v[12:15], v[150:153], v[206:209], v[12:15]
	s_setprio 0
	s_setprio 1
	v_mfma_f32_16x16x32_bf16 v[56:59], v[154:157], v[170:173], v[56:59]
	v_mfma_f32_16x16x32_bf16 v[52:55], v[162:165], v[170:173], v[52:55]
	v_mfma_f32_16x16x32_bf16 v[40:43], v[154:157], v[178:181], v[40:43]
	v_mfma_f32_16x16x32_bf16 v[36:39], v[162:165], v[178:181], v[36:39]
	v_mfma_f32_16x16x32_bf16 v[24:27], v[154:157], v[186:189], v[24:27]
	v_mfma_f32_16x16x32_bf16 v[20:23], v[162:165], v[186:189], v[20:23]
	v_mfma_f32_16x16x32_bf16 v[8:11], v[154:157], v[194:197], v[8:11]
	v_mfma_f32_16x16x32_bf16 v[4:7], v[162:165], v[194:197], v[4:7]
	v_mfma_f32_16x16x32_bf16 v[56:59], v[158:161], v[174:177], v[56:59]
	v_mfma_f32_16x16x32_bf16 v[52:55], v[166:169], v[174:177], v[52:55]
	v_mfma_f32_16x16x32_bf16 v[40:43], v[158:161], v[182:185], v[40:43]
	v_mfma_f32_16x16x32_bf16 v[36:39], v[166:169], v[182:185], v[36:39]
	v_mfma_f32_16x16x32_bf16 v[24:27], v[158:161], v[190:193], v[24:27]
	v_mfma_f32_16x16x32_bf16 v[20:23], v[166:169], v[190:193], v[20:23]
	v_mfma_f32_16x16x32_bf16 v[8:11], v[158:161], v[206:209], v[8:11]
	v_mfma_f32_16x16x32_bf16 v[4:7], v[166:169], v[206:209], v[4:7]
	s_setprio 0
	s_barrier
	s_cbranch_scc0 .LBB0_605

.LBB0_622:
	v_add_u32_e32 v144, 0x10000, v154
	v_add_u32_e32 v148, 0x14000, v154
	ds_read_b128 v[132:135], v144
	ds_read_b128 v[136:139], v144 offset:1024
	ds_read_b128 v[140:143], v144 offset:2048
	ds_read_b128 v[144:147], v144 offset:3072
	ds_read_b128 v[156:159], v148
	ds_read_b128 v[160:163], v148 offset:1024
	ds_read_b128 v[164:167], v148 offset:2048
	ds_read_b128 v[168:171], v148 offset:3072
	s_add_i32 s71, s28, 2
	s_cmp_eq_u32 s14, s28
	s_cselect_b32 s40, s21, s67
	s_cselect_b32 s41, s3, s68
	s_cselect_b32 s30, s66, s69
	s_cselect_b32 s31, s23, s70
	s_add_u32 s28, s40, 0x80
	s_addc_u32 s29, s41, 0
	ds_read_b128 v[172:175], v155
	ds_read_b128 v[176:179], v155 offset:1024
	ds_read_b128 v[180:183], v155 offset:2048
	ds_read_b128 v[184:187], v155 offset:3072
	ds_read_b128 v[188:191], v155 offset:4096
	ds_read_b128 v[192:195], v155 offset:5120
	ds_read_b128 v[206:209], v155 offset:6144
	ds_read_b128 v[210:213], v155 offset:7168
	s_add_u32 s72, s67, 0x1ff80
	s_addc_u32 s73, s68, 0
	s_mov_b32 m0, s15
	s_nop 0
	global_load_lds_dwordx4 v1, s[72:73]
	s_mov_b32 m0, s34
	s_nop 0
	global_load_lds_dwordx4 v150, s[72:73]
	s_waitcnt vmcnt(8)
	s_waitcnt lgkmcnt(0)
	s_barrier
	s_setprio 1
	s_waitcnt lgkmcnt(7)
	v_mfma_f32_16x16x32_bf16 v[124:127], v[132:135], v[172:175], v[124:127]
	v_mfma_f32_16x16x32_bf16 v[128:131], v[140:143], v[172:175], v[128:131]
	s_waitcnt lgkmcnt(5)
	v_mfma_f32_16x16x32_bf16 v[112:115], v[132:135], v[180:183], v[112:115]
	v_mfma_f32_16x16x32_bf16 v[108:111], v[140:143], v[180:183], v[108:111]
	s_waitcnt lgkmcnt(3)
	v_mfma_f32_16x16x32_bf16 v[96:99], v[132:135], v[188:191], v[96:99]
	v_mfma_f32_16x16x32_bf16 v[92:95], v[140:143], v[188:191], v[92:95]
	s_waitcnt lgkmcnt(1)
	v_mfma_f32_16x16x32_bf16 v[80:83], v[132:135], v[206:209], v[80:83]
	v_mfma_f32_16x16x32_bf16 v[76:79], v[140:143], v[206:209], v[76:79]
	v_mfma_f32_16x16x32_bf16 v[124:127], v[136:139], v[176:179], v[124:127]
	v_mfma_f32_16x16x32_bf16 v[128:131], v[144:147], v[176:179], v[128:131]
	v_mfma_f32_16x16x32_bf16 v[112:115], v[136:139], v[184:187], v[112:115]
	v_mfma_f32_16x16x32_bf16 v[108:111], v[144:147], v[184:187], v[108:111]
	v_mfma_f32_16x16x32_bf16 v[96:99], v[136:139], v[192:195], v[96:99]
	v_mfma_f32_16x16x32_bf16 v[92:95], v[144:147], v[192:195], v[92:95]
	s_waitcnt lgkmcnt(0)
	v_mfma_f32_16x16x32_bf16 v[80:83], v[136:139], v[210:213], v[80:83]
	v_mfma_f32_16x16x32_bf16 v[76:79], v[144:147], v[210:213], v[76:79]
	s_setprio 0
	s_setprio 1
	v_mfma_f32_16x16x32_bf16 v[120:123], v[156:159], v[172:175], v[120:123]
	v_mfma_f32_16x16x32_bf16 v[116:119], v[164:167], v[172:175], v[116:119]
	v_mfma_f32_16x16x32_bf16 v[104:107], v[156:159], v[180:183], v[104:107]
	v_mfma_f32_16x16x32_bf16 v[100:103], v[164:167], v[180:183], v[100:103]
	v_mfma_f32_16x16x32_bf16 v[88:91], v[156:159], v[188:191], v[88:91]
	v_mfma_f32_16x16x32_bf16 v[84:87], v[164:167], v[188:191], v[84:87]
	v_mfma_f32_16x16x32_bf16 v[72:75], v[156:159], v[206:209], v[72:75]
	v_mfma_f32_16x16x32_bf16 v[68:71], v[164:167], v[206:209], v[68:71]
	v_mfma_f32_16x16x32_bf16 v[120:123], v[160:163], v[176:179], v[120:123]
	v_mfma_f32_16x16x32_bf16 v[116:119], v[168:171], v[176:179], v[116:119]
	v_mfma_f32_16x16x32_bf16 v[104:107], v[160:163], v[184:187], v[104:107]
	v_mfma_f32_16x16x32_bf16 v[100:103], v[168:171], v[184:187], v[100:103]
	v_mfma_f32_16x16x32_bf16 v[88:91], v[160:163], v[192:195], v[88:91]
	v_mfma_f32_16x16x32_bf16 v[84:87], v[168:171], v[192:195], v[84:87]
	v_mfma_f32_16x16x32_bf16 v[72:75], v[160:163], v[210:213], v[72:75]
	v_mfma_f32_16x16x32_bf16 v[68:71], v[168:171], v[210:213], v[68:71]
	s_setprio 0
	s_barrier
	ds_read_b128 v[172:175], v155 offset:16384
	ds_read_b128 v[176:179], v155 offset:17408
	ds_read_b128 v[180:183], v155 offset:18432
	ds_read_b128 v[184:187], v155 offset:19456
	ds_read_b128 v[188:191], v155 offset:20480
	ds_read_b128 v[192:195], v155 offset:21504
	ds_read_b128 v[206:209], v155 offset:22528
	ds_read_b128 v[210:213], v155 offset:23552
	s_mov_b32 m0, s50
	s_nop 0
	global_load_lds_dwordx4 v2, s[30:31]
	s_mov_b32 m0, s51
	s_nop 0
	global_load_lds_dwordx4 v151, s[30:31]
	s_add_u32 s72, s30, 0x20000
	s_addc_u32 s73, s31, 0
	s_mov_b32 m0, s55
	s_nop 0
	global_load_lds_dwordx4 v2, s[72:73]
	s_mov_b32 m0, s56
	s_nop 0
	global_load_lds_dwordx4 v151, s[72:73]
	s_mov_b32 m0, s1
	s_nop 0
	global_load_lds_dwordx4 v1, s[40:41]
	s_mov_b32 m0, s57
	s_nop 0
	global_load_lds_dwordx4 v150, s[40:41]
	s_waitcnt vmcnt(8)
	s_waitcnt lgkmcnt(0)
	s_barrier
	s_setprio 1
	s_waitcnt lgkmcnt(7)
	v_mfma_f32_16x16x32_bf16 v[64:67], v[132:135], v[172:175], v[64:67]
	v_mfma_f32_16x16x32_bf16 v[60:63], v[140:143], v[172:175], v[60:63]
	s_waitcnt lgkmcnt(5)
	v_mfma_f32_16x16x32_bf16 v[48:51], v[132:135], v[180:183], v[48:51]
	v_mfma_f32_16x16x32_bf16 v[44:47], v[140:143], v[180:183], v[44:47]
	s_waitcnt lgkmcnt(3)
	v_mfma_f32_16x16x32_bf16 v[32:35], v[132:135], v[188:191], v[32:35]
	v_mfma_f32_16x16x32_bf16 v[28:31], v[140:143], v[188:191], v[28:31]
	s_waitcnt lgkmcnt(1)
	v_mfma_f32_16x16x32_bf16 v[16:19], v[132:135], v[206:209], v[16:19]
	v_mfma_f32_16x16x32_bf16 v[12:15], v[140:143], v[206:209], v[12:15]
	v_mfma_f32_16x16x32_bf16 v[64:67], v[136:139], v[176:179], v[64:67]
	v_mfma_f32_16x16x32_bf16 v[60:63], v[144:147], v[176:179], v[60:63]
	v_mfma_f32_16x16x32_bf16 v[48:51], v[136:139], v[184:187], v[48:51]
	v_mfma_f32_16x16x32_bf16 v[44:47], v[144:147], v[184:187], v[44:47]
	v_mfma_f32_16x16x32_bf16 v[32:35], v[136:139], v[192:195], v[32:35]
	v_mfma_f32_16x16x32_bf16 v[28:31], v[144:147], v[192:195], v[28:31]
	s_waitcnt lgkmcnt(0)
	v_mfma_f32_16x16x32_bf16 v[16:19], v[136:139], v[210:213], v[16:19]
	v_mfma_f32_16x16x32_bf16 v[12:15], v[144:147], v[210:213], v[12:15]
	s_setprio 0
	s_setprio 1
	v_mfma_f32_16x16x32_bf16 v[56:59], v[156:159], v[172:175], v[56:59]
	v_mfma_f32_16x16x32_bf16 v[52:55], v[164:167], v[172:175], v[52:55]
	v_mfma_f32_16x16x32_bf16 v[40:43], v[156:159], v[180:183], v[40:43]
	v_mfma_f32_16x16x32_bf16 v[36:39], v[164:167], v[180:183], v[36:39]
	v_mfma_f32_16x16x32_bf16 v[24:27], v[156:159], v[188:191], v[24:27]
	v_mfma_f32_16x16x32_bf16 v[20:23], v[164:167], v[188:191], v[20:23]
	v_mfma_f32_16x16x32_bf16 v[8:11], v[156:159], v[206:209], v[8:11]
	v_mfma_f32_16x16x32_bf16 v[4:7], v[164:167], v[206:209], v[4:7]
	v_mfma_f32_16x16x32_bf16 v[56:59], v[160:163], v[176:179], v[56:59]
	v_mfma_f32_16x16x32_bf16 v[52:55], v[168:171], v[176:179], v[52:55]
	v_mfma_f32_16x16x32_bf16 v[40:43], v[160:163], v[184:187], v[40:43]
	v_mfma_f32_16x16x32_bf16 v[36:39], v[168:171], v[184:187], v[36:39]
	v_mfma_f32_16x16x32_bf16 v[24:27], v[160:163], v[192:195], v[24:27]
	v_mfma_f32_16x16x32_bf16 v[20:23], v[168:171], v[192:195], v[20:23]
	v_mfma_f32_16x16x32_bf16 v[8:11], v[160:163], v[210:213], v[8:11]
	v_mfma_f32_16x16x32_bf16 v[4:7], v[168:171], v[210:213], v[4:7]
	s_setprio 0
	s_barrier
	v_add_u32_e32 v144, 0x18000, v154
	v_add_u32_e32 v148, 0x1c000, v154
	ds_read_b128 v[132:135], v144
	ds_read_b128 v[136:139], v144 offset:1024
	ds_read_b128 v[140:143], v144 offset:2048
	ds_read_b128 v[144:147], v144 offset:3072
	ds_read_b128 v[156:159], v148
	ds_read_b128 v[160:163], v148 offset:1024
	ds_read_b128 v[164:167], v148 offset:2048
	ds_read_b128 v[168:171], v148 offset:3072
	ds_read_b128 v[172:175], v155 offset:32768
	ds_read_b128 v[176:179], v155 offset:33792
	ds_read_b128 v[180:183], v155 offset:34816
	ds_read_b128 v[184:187], v155 offset:35840
	ds_read_b128 v[188:191], v155 offset:36864
	ds_read_b128 v[192:195], v155 offset:37888
	ds_read_b128 v[206:209], v155 offset:38912
	ds_read_b128 v[210:213], v155 offset:39936
	s_add_u32 s40, s40, 0x20000
	s_addc_u32 s41, s41, 0
	s_mov_b32 m0, s58
	s_nop 0
	global_load_lds_dwordx4 v1, s[40:41]
	s_mov_b32 m0, s59
	s_nop 0
	global_load_lds_dwordx4 v150, s[40:41]
	s_waitcnt vmcnt(8)
	s_waitcnt lgkmcnt(0)
	s_barrier
	s_setprio 1
	s_waitcnt lgkmcnt(7)
	v_mfma_f32_16x16x32_bf16 v[124:127], v[132:135], v[172:175], v[124:127]
	v_mfma_f32_16x16x32_bf16 v[128:131], v[140:143], v[172:175], v[128:131]
	s_waitcnt lgkmcnt(5)
	v_mfma_f32_16x16x32_bf16 v[112:115], v[132:135], v[180:183], v[112:115]
	v_mfma_f32_16x16x32_bf16 v[108:111], v[140:143], v[180:183], v[108:111]
	s_waitcnt lgkmcnt(3)
	v_mfma_f32_16x16x32_bf16 v[96:99], v[132:135], v[188:191], v[96:99]
	v_mfma_f32_16x16x32_bf16 v[92:95], v[140:143], v[188:191], v[92:95]
	s_waitcnt lgkmcnt(1)
	v_mfma_f32_16x16x32_bf16 v[80:83], v[132:135], v[206:209], v[80:83]
	v_mfma_f32_16x16x32_bf16 v[76:79], v[140:143], v[206:209], v[76:79]
	v_mfma_f32_16x16x32_bf16 v[124:127], v[136:139], v[176:179], v[124:127]
	v_mfma_f32_16x16x32_bf16 v[128:131], v[144:147], v[176:179], v[128:131]
	v_mfma_f32_16x16x32_bf16 v[112:115], v[136:139], v[184:187], v[112:115]
	v_mfma_f32_16x16x32_bf16 v[108:111], v[144:147], v[184:187], v[108:111]
	v_mfma_f32_16x16x32_bf16 v[96:99], v[136:139], v[192:195], v[96:99]
	v_mfma_f32_16x16x32_bf16 v[92:95], v[144:147], v[192:195], v[92:95]
	s_waitcnt lgkmcnt(0)
	v_mfma_f32_16x16x32_bf16 v[80:83], v[136:139], v[210:213], v[80:83]
	v_mfma_f32_16x16x32_bf16 v[76:79], v[144:147], v[210:213], v[76:79]
	s_setprio 0
	s_setprio 1
	v_mfma_f32_16x16x32_bf16 v[120:123], v[156:159], v[172:175], v[120:123]
	v_mfma_f32_16x16x32_bf16 v[116:119], v[164:167], v[172:175], v[116:119]
	v_mfma_f32_16x16x32_bf16 v[104:107], v[156:159], v[180:183], v[104:107]
	v_mfma_f32_16x16x32_bf16 v[100:103], v[164:167], v[180:183], v[100:103]
	v_mfma_f32_16x16x32_bf16 v[88:91], v[156:159], v[188:191], v[88:91]
	v_mfma_f32_16x16x32_bf16 v[84:87], v[164:167], v[188:191], v[84:87]
	v_mfma_f32_16x16x32_bf16 v[72:75], v[156:159], v[206:209], v[72:75]
	v_mfma_f32_16x16x32_bf16 v[68:71], v[164:167], v[206:209], v[68:71]
	v_mfma_f32_16x16x32_bf16 v[120:123], v[160:163], v[176:179], v[120:123]
	v_mfma_f32_16x16x32_bf16 v[116:119], v[168:171], v[176:179], v[116:119]
	v_mfma_f32_16x16x32_bf16 v[104:107], v[160:163], v[184:187], v[104:107]
	v_mfma_f32_16x16x32_bf16 v[100:103], v[168:171], v[184:187], v[100:103]
	v_mfma_f32_16x16x32_bf16 v[88:91], v[160:163], v[192:195], v[88:91]
	v_mfma_f32_16x16x32_bf16 v[84:87], v[168:171], v[192:195], v[84:87]
	v_mfma_f32_16x16x32_bf16 v[72:75], v[160:163], v[210:213], v[72:75]
	v_mfma_f32_16x16x32_bf16 v[68:71], v[168:171], v[210:213], v[68:71]
	s_setprio 0
	s_barrier
	ds_read_b128 v[172:175], v155 offset:49152
	ds_read_b128 v[176:179], v155 offset:50176
	ds_read_b128 v[180:183], v155 offset:51200
	ds_read_b128 v[184:187], v155 offset:52224
	ds_read_b128 v[188:191], v155 offset:53248
	ds_read_b128 v[192:195], v155 offset:54272
	ds_read_b128 v[206:209], v155 offset:55296
	ds_read_b128 v[210:213], v155 offset:56320
	s_add_u32 s40, s30, 0x80
	s_addc_u32 s41, s31, 0
	s_mov_b32 m0, s61
	s_nop 0
	global_load_lds_dwordx4 v2, s[40:41]
	s_add_u32 s30, s30, 0x20080
	s_mov_b32 m0, s62
	s_nop 0
	global_load_lds_dwordx4 v151, s[40:41]
	s_addc_u32 s31, s31, 0
	s_mov_b32 m0, s65
	s_nop 0
	global_load_lds_dwordx4 v2, s[30:31]
	s_mov_b32 m0, s33
	s_nop 0
	global_load_lds_dwordx4 v151, s[30:31]
	s_mov_b32 m0, s63
	s_nop 0
	global_load_lds_dwordx4 v1, s[28:29]
	s_mov_b32 m0, s64
	s_nop 0
	global_load_lds_dwordx4 v150, s[28:29]
	s_waitcnt vmcnt(8)
	s_waitcnt lgkmcnt(0)
	s_barrier
	s_setprio 1
	s_waitcnt lgkmcnt(7)
	v_mfma_f32_16x16x32_bf16 v[64:67], v[132:135], v[172:175], v[64:67]
	v_mfma_f32_16x16x32_bf16 v[60:63], v[140:143], v[172:175], v[60:63]
	s_add_u32 s67, s67, 0x100
	s_waitcnt lgkmcnt(5)
	v_mfma_f32_16x16x32_bf16 v[48:51], v[132:135], v[180:183], v[48:51]
	s_addc_u32 s68, s68, 0
	v_mfma_f32_16x16x32_bf16 v[44:47], v[140:143], v[180:183], v[44:47]
	s_add_u32 s69, s69, 0x100
	s_waitcnt lgkmcnt(3)
	v_mfma_f32_16x16x32_bf16 v[32:35], v[132:135], v[188:191], v[32:35]
	s_addc_u32 s70, s70, 0
	v_mfma_f32_16x16x32_bf16 v[28:31], v[140:143], v[188:191], v[28:31]
	s_mov_b32 s28, s71
	s_waitcnt lgkmcnt(1)
	v_mfma_f32_16x16x32_bf16 v[16:19], v[132:135], v[206:209], v[16:19]
	s_cmp_ge_i32 s71, s60
	v_mfma_f32_16x16x32_bf16 v[12:15], v[140:143], v[206:209], v[12:15]
	v_mfma_f32_16x16x32_bf16 v[64:67], v[136:139], v[176:179], v[64:67]
	v_mfma_f32_16x16x32_bf16 v[60:63], v[144:147], v[176:179], v[60:63]
	v_mfma_f32_16x16x32_bf16 v[48:51], v[136:139], v[184:187], v[48:51]
	v_mfma_f32_16x16x32_bf16 v[44:47], v[144:147], v[184:187], v[44:47]
	v_mfma_f32_16x16x32_bf16 v[32:35], v[136:139], v[192:195], v[32:35]
	v_mfma_f32_16x16x32_bf16 v[28:31], v[144:147], v[192:195], v[28:31]
	s_waitcnt lgkmcnt(0)
	v_mfma_f32_16x16x32_bf16 v[16:19], v[136:139], v[210:213], v[16:19]
	v_mfma_f32_16x16x32_bf16 v[12:15], v[144:147], v[210:213], v[12:15]
	s_setprio 0
	s_setprio 1
	v_mfma_f32_16x16x32_bf16 v[56:59], v[156:159], v[172:175], v[56:59]
	v_mfma_f32_16x16x32_bf16 v[52:55], v[164:167], v[172:175], v[52:55]
	v_mfma_f32_16x16x32_bf16 v[40:43], v[156:159], v[180:183], v[40:43]
	v_mfma_f32_16x16x32_bf16 v[36:39], v[164:167], v[180:183], v[36:39]
	v_mfma_f32_16x16x32_bf16 v[24:27], v[156:159], v[188:191], v[24:27]
	v_mfma_f32_16x16x32_bf16 v[20:23], v[164:167], v[188:191], v[20:23]
	v_mfma_f32_16x16x32_bf16 v[8:11], v[156:159], v[206:209], v[8:11]
	v_mfma_f32_16x16x32_bf16 v[4:7], v[164:167], v[206:209], v[4:7]
	v_mfma_f32_16x16x32_bf16 v[56:59], v[160:163], v[176:179], v[56:59]
	v_mfma_f32_16x16x32_bf16 v[52:55], v[168:171], v[176:179], v[52:55]
	v_mfma_f32_16x16x32_bf16 v[40:43], v[160:163], v[184:187], v[40:43]
	v_mfma_f32_16x16x32_bf16 v[36:39], v[168:171], v[184:187], v[36:39]
	v_mfma_f32_16x16x32_bf16 v[24:27], v[160:163], v[192:195], v[24:27]
	v_mfma_f32_16x16x32_bf16 v[20:23], v[168:171], v[192:195], v[20:23]
	v_mfma_f32_16x16x32_bf16 v[8:11], v[160:163], v[210:213], v[8:11]
	v_mfma_f32_16x16x32_bf16 v[4:7], v[168:171], v[210:213], v[4:7]
	s_setprio 0
	s_barrier
	s_cbranch_scc0 .LBB0_622

.LBB0_1023:
	v_add_u32_e32 v144, 0x10000, v2
	v_add_u32_e32 v160, 0x14000, v2
	ds_read_b128 v[132:135], v144
	ds_read_b128 v[136:139], v144 offset:1024
	ds_read_b128 v[140:143], v144 offset:2048
	ds_read_b128 v[144:147], v144 offset:3072
	ds_read_b128 v[148:151], v160
	ds_read_b128 v[152:155], v160 offset:1024
	ds_read_b128 v[156:159], v160 offset:2048
	ds_read_b128 v[160:163], v160 offset:3072
	s_add_i32 s34, s0, 2
	s_cmp_eq_u32 s68, s0
	s_cselect_b32 s30, s13, s19
	s_cselect_b32 s31, s1, s25
	s_cselect_b32 s28, s15, s27
	s_cselect_b32 s29, s14, s33
	s_add_u32 s2, s30, 0x80
	s_addc_u32 s3, s31, 0
	ds_read_b128 v[164:167], v195
	ds_read_b128 v[168:171], v195 offset:1024
	ds_read_b128 v[172:175], v195 offset:2048
	ds_read_b128 v[176:179], v195 offset:3072
	ds_read_b128 v[196:199], v195 offset:4096
	ds_read_b128 v[202:205], v195 offset:5120
	ds_read_b128 v[206:209], v195 offset:6144
	ds_read_b128 v[210:213], v195 offset:7168
	s_add_u32 s72, s19, 0x7ff80
	s_addc_u32 s73, s25, 0
	s_mov_b32 m0, s69
	s_nop 0
	global_load_lds_dwordx4 v1, s[72:73]
	s_mov_b32 m0, s70
	s_nop 0
	global_load_lds_dwordx4 v191, s[72:73]
	s_waitcnt vmcnt(8)
	s_waitcnt lgkmcnt(0)
	s_barrier
	s_setprio 1
	s_waitcnt lgkmcnt(7)
	v_mfma_f32_16x16x32_bf16 v[128:131], v[132:135], v[164:167], v[128:131]
	v_mfma_f32_16x16x32_bf16 v[124:127], v[140:143], v[164:167], v[124:127]
	s_waitcnt lgkmcnt(5)
	v_mfma_f32_16x16x32_bf16 v[112:115], v[132:135], v[172:175], v[112:115]
	v_mfma_f32_16x16x32_bf16 v[108:111], v[140:143], v[172:175], v[108:111]
	s_waitcnt lgkmcnt(3)
	v_mfma_f32_16x16x32_bf16 v[96:99], v[132:135], v[196:199], v[96:99]
	v_mfma_f32_16x16x32_bf16 v[92:95], v[140:143], v[196:199], v[92:95]
	s_waitcnt lgkmcnt(1)
	v_mfma_f32_16x16x32_bf16 v[80:83], v[132:135], v[206:209], v[80:83]
	v_mfma_f32_16x16x32_bf16 v[76:79], v[140:143], v[206:209], v[76:79]
	v_mfma_f32_16x16x32_bf16 v[128:131], v[136:139], v[168:171], v[128:131]
	v_mfma_f32_16x16x32_bf16 v[124:127], v[144:147], v[168:171], v[124:127]
	v_mfma_f32_16x16x32_bf16 v[112:115], v[136:139], v[176:179], v[112:115]
	v_mfma_f32_16x16x32_bf16 v[108:111], v[144:147], v[176:179], v[108:111]
	v_mfma_f32_16x16x32_bf16 v[96:99], v[136:139], v[202:205], v[96:99]
	v_mfma_f32_16x16x32_bf16 v[92:95], v[144:147], v[202:205], v[92:95]
	s_waitcnt lgkmcnt(0)
	v_mfma_f32_16x16x32_bf16 v[80:83], v[136:139], v[210:213], v[80:83]
	v_mfma_f32_16x16x32_bf16 v[76:79], v[144:147], v[210:213], v[76:79]
	s_setprio 0
	s_setprio 1
	v_mfma_f32_16x16x32_bf16 v[120:123], v[148:151], v[164:167], v[120:123]
	v_mfma_f32_16x16x32_bf16 v[116:119], v[156:159], v[164:167], v[116:119]
	v_mfma_f32_16x16x32_bf16 v[104:107], v[148:151], v[172:175], v[104:107]
	v_mfma_f32_16x16x32_bf16 v[100:103], v[156:159], v[172:175], v[100:103]
	v_mfma_f32_16x16x32_bf16 v[88:91], v[148:151], v[196:199], v[88:91]
	v_mfma_f32_16x16x32_bf16 v[84:87], v[156:159], v[196:199], v[84:87]
	v_mfma_f32_16x16x32_bf16 v[72:75], v[148:151], v[206:209], v[72:75]
	v_mfma_f32_16x16x32_bf16 v[68:71], v[156:159], v[206:209], v[68:71]
	v_mfma_f32_16x16x32_bf16 v[120:123], v[152:155], v[168:171], v[120:123]
	v_mfma_f32_16x16x32_bf16 v[116:119], v[160:163], v[168:171], v[116:119]
	v_mfma_f32_16x16x32_bf16 v[104:107], v[152:155], v[176:179], v[104:107]
	v_mfma_f32_16x16x32_bf16 v[100:103], v[160:163], v[176:179], v[100:103]
	v_mfma_f32_16x16x32_bf16 v[88:91], v[152:155], v[202:205], v[88:91]
	v_mfma_f32_16x16x32_bf16 v[84:87], v[160:163], v[202:205], v[84:87]
	v_mfma_f32_16x16x32_bf16 v[72:75], v[152:155], v[210:213], v[72:75]
	v_mfma_f32_16x16x32_bf16 v[68:71], v[160:163], v[210:213], v[68:71]
	s_setprio 0
	s_barrier
	ds_read_b128 v[164:167], v195 offset:16384
	ds_read_b128 v[168:171], v195 offset:17408
	ds_read_b128 v[172:175], v195 offset:18432
	ds_read_b128 v[176:179], v195 offset:19456
	ds_read_b128 v[196:199], v195 offset:20480
	ds_read_b128 v[202:205], v195 offset:21504
	ds_read_b128 v[206:209], v195 offset:22528
	ds_read_b128 v[210:213], v195 offset:23552
	s_mov_b32 m0, s51
	s_nop 0
	global_load_lds_dwordx4 v190, s[28:29]
	s_add_u32 s72, s28, 0x80000
	s_mov_b32 m0, s52
	s_nop 0
	global_load_lds_dwordx4 v192, s[28:29]
	s_addc_u32 s73, s29, 0
	s_mov_b32 m0, s53
	s_nop 0
	global_load_lds_dwordx4 v190, s[72:73]
	s_mov_b32 m0, s54
	s_nop 0
	global_load_lds_dwordx4 v192, s[72:73]
	s_mov_b32 m0, s50
	s_nop 0
	global_load_lds_dwordx4 v1, s[30:31]
	s_mov_b32 m0, s55
	s_nop 0
	global_load_lds_dwordx4 v191, s[30:31]
	s_waitcnt vmcnt(8)
	s_waitcnt lgkmcnt(0)
	s_barrier
	s_setprio 1
	s_waitcnt lgkmcnt(7)
	v_mfma_f32_16x16x32_bf16 v[64:67], v[132:135], v[164:167], v[64:67]
	v_mfma_f32_16x16x32_bf16 v[60:63], v[140:143], v[164:167], v[60:63]
	s_waitcnt lgkmcnt(5)
	v_mfma_f32_16x16x32_bf16 v[48:51], v[132:135], v[172:175], v[48:51]
	v_mfma_f32_16x16x32_bf16 v[44:47], v[140:143], v[172:175], v[44:47]
	s_waitcnt lgkmcnt(3)
	v_mfma_f32_16x16x32_bf16 v[32:35], v[132:135], v[196:199], v[32:35]
	v_mfma_f32_16x16x32_bf16 v[28:31], v[140:143], v[196:199], v[28:31]
	s_waitcnt lgkmcnt(1)
	v_mfma_f32_16x16x32_bf16 v[16:19], v[132:135], v[206:209], v[16:19]
	v_mfma_f32_16x16x32_bf16 v[12:15], v[140:143], v[206:209], v[12:15]
	v_mfma_f32_16x16x32_bf16 v[64:67], v[136:139], v[168:171], v[64:67]
	v_mfma_f32_16x16x32_bf16 v[60:63], v[144:147], v[168:171], v[60:63]
	v_mfma_f32_16x16x32_bf16 v[48:51], v[136:139], v[176:179], v[48:51]
	v_mfma_f32_16x16x32_bf16 v[44:47], v[144:147], v[176:179], v[44:47]
	v_mfma_f32_16x16x32_bf16 v[32:35], v[136:139], v[202:205], v[32:35]
	v_mfma_f32_16x16x32_bf16 v[28:31], v[144:147], v[202:205], v[28:31]
	s_waitcnt lgkmcnt(0)
	v_mfma_f32_16x16x32_bf16 v[16:19], v[136:139], v[210:213], v[16:19]
	v_mfma_f32_16x16x32_bf16 v[12:15], v[144:147], v[210:213], v[12:15]
	s_setprio 0
	s_setprio 1
	v_mfma_f32_16x16x32_bf16 v[56:59], v[148:151], v[164:167], v[56:59]
	v_mfma_f32_16x16x32_bf16 v[52:55], v[156:159], v[164:167], v[52:55]
	v_mfma_f32_16x16x32_bf16 v[40:43], v[148:151], v[172:175], v[40:43]
	v_mfma_f32_16x16x32_bf16 v[36:39], v[156:159], v[172:175], v[36:39]
	v_mfma_f32_16x16x32_bf16 v[24:27], v[148:151], v[196:199], v[24:27]
	v_mfma_f32_16x16x32_bf16 v[20:23], v[156:159], v[196:199], v[20:23]
	v_mfma_f32_16x16x32_bf16 v[8:11], v[148:151], v[206:209], v[8:11]
	v_mfma_f32_16x16x32_bf16 v[4:7], v[156:159], v[206:209], v[4:7]
	v_mfma_f32_16x16x32_bf16 v[56:59], v[152:155], v[168:171], v[56:59]
	v_mfma_f32_16x16x32_bf16 v[52:55], v[160:163], v[168:171], v[52:55]
	v_mfma_f32_16x16x32_bf16 v[40:43], v[152:155], v[176:179], v[40:43]
	v_mfma_f32_16x16x32_bf16 v[36:39], v[160:163], v[176:179], v[36:39]
	v_mfma_f32_16x16x32_bf16 v[24:27], v[152:155], v[202:205], v[24:27]
	v_mfma_f32_16x16x32_bf16 v[20:23], v[160:163], v[202:205], v[20:23]
	v_mfma_f32_16x16x32_bf16 v[8:11], v[152:155], v[210:213], v[8:11]
	v_mfma_f32_16x16x32_bf16 v[4:7], v[160:163], v[210:213], v[4:7]
	s_setprio 0
	s_barrier
	v_add_u32_e32 v144, 0x18000, v2
	v_add_u32_e32 v160, 0x1c000, v2
	ds_read_b128 v[132:135], v144
	ds_read_b128 v[136:139], v144 offset:1024
	ds_read_b128 v[140:143], v144 offset:2048
	ds_read_b128 v[144:147], v144 offset:3072
	ds_read_b128 v[148:151], v160
	ds_read_b128 v[152:155], v160 offset:1024
	ds_read_b128 v[156:159], v160 offset:2048
	ds_read_b128 v[160:163], v160 offset:3072
	ds_read_b128 v[164:167], v195 offset:32768
	ds_read_b128 v[168:171], v195 offset:33792
	ds_read_b128 v[172:175], v195 offset:34816
	ds_read_b128 v[176:179], v195 offset:35840
	ds_read_b128 v[196:199], v195 offset:36864
	ds_read_b128 v[202:205], v195 offset:37888
	ds_read_b128 v[206:209], v195 offset:38912
	ds_read_b128 v[210:213], v195 offset:39936
	s_add_u32 s30, s30, 0x80000
	s_addc_u32 s31, s31, 0
	s_mov_b32 m0, s56
	s_nop 0
	global_load_lds_dwordx4 v1, s[30:31]
	s_mov_b32 m0, s57
	s_nop 0
	global_load_lds_dwordx4 v191, s[30:31]
	s_waitcnt vmcnt(8)
	s_waitcnt lgkmcnt(0)
	s_barrier
	s_setprio 1
	s_waitcnt lgkmcnt(7)
	v_mfma_f32_16x16x32_bf16 v[128:131], v[132:135], v[164:167], v[128:131]
	v_mfma_f32_16x16x32_bf16 v[124:127], v[140:143], v[164:167], v[124:127]
	s_waitcnt lgkmcnt(5)
	v_mfma_f32_16x16x32_bf16 v[112:115], v[132:135], v[172:175], v[112:115]
	v_mfma_f32_16x16x32_bf16 v[108:111], v[140:143], v[172:175], v[108:111]
	s_waitcnt lgkmcnt(3)
	v_mfma_f32_16x16x32_bf16 v[96:99], v[132:135], v[196:199], v[96:99]
	v_mfma_f32_16x16x32_bf16 v[92:95], v[140:143], v[196:199], v[92:95]
	s_waitcnt lgkmcnt(1)
	v_mfma_f32_16x16x32_bf16 v[80:83], v[132:135], v[206:209], v[80:83]
	v_mfma_f32_16x16x32_bf16 v[76:79], v[140:143], v[206:209], v[76:79]
	v_mfma_f32_16x16x32_bf16 v[128:131], v[136:139], v[168:171], v[128:131]
	v_mfma_f32_16x16x32_bf16 v[124:127], v[144:147], v[168:171], v[124:127]
	v_mfma_f32_16x16x32_bf16 v[112:115], v[136:139], v[176:179], v[112:115]
	v_mfma_f32_16x16x32_bf16 v[108:111], v[144:147], v[176:179], v[108:111]
	v_mfma_f32_16x16x32_bf16 v[96:99], v[136:139], v[202:205], v[96:99]
	v_mfma_f32_16x16x32_bf16 v[92:95], v[144:147], v[202:205], v[92:95]
	s_waitcnt lgkmcnt(0)
	v_mfma_f32_16x16x32_bf16 v[80:83], v[136:139], v[210:213], v[80:83]
	v_mfma_f32_16x16x32_bf16 v[76:79], v[144:147], v[210:213], v[76:79]
	s_setprio 0
	s_setprio 1
	v_mfma_f32_16x16x32_bf16 v[120:123], v[148:151], v[164:167], v[120:123]
	v_mfma_f32_16x16x32_bf16 v[116:119], v[156:159], v[164:167], v[116:119]
	v_mfma_f32_16x16x32_bf16 v[104:107], v[148:151], v[172:175], v[104:107]
	v_mfma_f32_16x16x32_bf16 v[100:103], v[156:159], v[172:175], v[100:103]
	v_mfma_f32_16x16x32_bf16 v[88:91], v[148:151], v[196:199], v[88:91]
	v_mfma_f32_16x16x32_bf16 v[84:87], v[156:159], v[196:199], v[84:87]
	v_mfma_f32_16x16x32_bf16 v[72:75], v[148:151], v[206:209], v[72:75]
	v_mfma_f32_16x16x32_bf16 v[68:71], v[156:159], v[206:209], v[68:71]
	v_mfma_f32_16x16x32_bf16 v[120:123], v[152:155], v[168:171], v[120:123]
	v_mfma_f32_16x16x32_bf16 v[116:119], v[160:163], v[168:171], v[116:119]
	v_mfma_f32_16x16x32_bf16 v[104:107], v[152:155], v[176:179], v[104:107]
	v_mfma_f32_16x16x32_bf16 v[100:103], v[160:163], v[176:179], v[100:103]
	v_mfma_f32_16x16x32_bf16 v[88:91], v[152:155], v[202:205], v[88:91]
	v_mfma_f32_16x16x32_bf16 v[84:87], v[160:163], v[202:205], v[84:87]
	v_mfma_f32_16x16x32_bf16 v[72:75], v[152:155], v[210:213], v[72:75]
	v_mfma_f32_16x16x32_bf16 v[68:71], v[160:163], v[210:213], v[68:71]
	s_setprio 0
	s_barrier
	ds_read_b128 v[164:167], v195 offset:49152
	ds_read_b128 v[168:171], v195 offset:50176
	ds_read_b128 v[172:175], v195 offset:51200
	ds_read_b128 v[176:179], v195 offset:52224
	ds_read_b128 v[196:199], v195 offset:53248
	ds_read_b128 v[202:205], v195 offset:54272
	ds_read_b128 v[206:209], v195 offset:55296
	ds_read_b128 v[210:213], v195 offset:56320
	s_add_u32 s30, s28, 0x80
	s_addc_u32 s31, s29, 0
	s_mov_b32 m0, s62
	s_nop 0
	global_load_lds_dwordx4 v190, s[30:31]
	s_add_u32 s28, s28, 0x80080
	s_mov_b32 m0, s63
	s_nop 0
	global_load_lds_dwordx4 v192, s[30:31]
	s_addc_u32 s29, s29, 0
	s_mov_b32 m0, s66
	s_nop 0
	global_load_lds_dwordx4 v190, s[28:29]
	s_mov_b32 m0, s67
	s_nop 0
	global_load_lds_dwordx4 v192, s[28:29]
	s_mov_b32 m0, s64
	s_nop 0
	global_load_lds_dwordx4 v1, s[2:3]
	s_mov_b32 m0, s65
	s_nop 0
	global_load_lds_dwordx4 v191, s[2:3]
	s_waitcnt vmcnt(8)
	s_waitcnt lgkmcnt(0)
	s_barrier
	s_setprio 1
	s_waitcnt lgkmcnt(7)
	v_mfma_f32_16x16x32_bf16 v[64:67], v[132:135], v[164:167], v[64:67]
	v_mfma_f32_16x16x32_bf16 v[60:63], v[140:143], v[164:167], v[60:63]
	s_add_u32 s19, s19, 0x100
	s_waitcnt lgkmcnt(5)
	v_mfma_f32_16x16x32_bf16 v[48:51], v[132:135], v[172:175], v[48:51]
	s_addc_u32 s25, s25, 0
	v_mfma_f32_16x16x32_bf16 v[44:47], v[140:143], v[172:175], v[44:47]
	s_add_u32 s27, s27, 0x100
	s_waitcnt lgkmcnt(3)
	v_mfma_f32_16x16x32_bf16 v[32:35], v[132:135], v[196:199], v[32:35]
	s_addc_u32 s33, s33, 0
	v_mfma_f32_16x16x32_bf16 v[28:31], v[140:143], v[196:199], v[28:31]
	s_mov_b64 s[2:3], 0x40000
	s_waitcnt lgkmcnt(1)
	v_mfma_f32_16x16x32_bf16 v[16:19], v[132:135], v[206:209], v[16:19]
	v_lshl_add_u64 v[180:181], v[180:181], 0, s[2:3]
	v_mfma_f32_16x16x32_bf16 v[12:15], v[140:143], v[206:209], v[12:15]
	s_cmp_ge_i32 s34, s61
	v_mfma_f32_16x16x32_bf16 v[64:67], v[136:139], v[168:171], v[64:67]
	v_mfma_f32_16x16x32_bf16 v[60:63], v[144:147], v[168:171], v[60:63]
	v_mfma_f32_16x16x32_bf16 v[48:51], v[136:139], v[176:179], v[48:51]
	v_mfma_f32_16x16x32_bf16 v[44:47], v[144:147], v[176:179], v[44:47]
	v_mfma_f32_16x16x32_bf16 v[32:35], v[136:139], v[202:205], v[32:35]
	v_mfma_f32_16x16x32_bf16 v[28:31], v[144:147], v[202:205], v[28:31]
	s_waitcnt lgkmcnt(0)
	v_mfma_f32_16x16x32_bf16 v[16:19], v[136:139], v[210:213], v[16:19]
	v_mfma_f32_16x16x32_bf16 v[12:15], v[144:147], v[210:213], v[12:15]
	s_setprio 0
	s_setprio 1
	v_mfma_f32_16x16x32_bf16 v[56:59], v[148:151], v[164:167], v[56:59]
	v_mfma_f32_16x16x32_bf16 v[52:55], v[156:159], v[164:167], v[52:55]
	v_mfma_f32_16x16x32_bf16 v[40:43], v[148:151], v[172:175], v[40:43]
	v_mfma_f32_16x16x32_bf16 v[36:39], v[156:159], v[172:175], v[36:39]
	v_mfma_f32_16x16x32_bf16 v[24:27], v[148:151], v[196:199], v[24:27]
	v_mfma_f32_16x16x32_bf16 v[20:23], v[156:159], v[196:199], v[20:23]
	v_mfma_f32_16x16x32_bf16 v[8:11], v[148:151], v[206:209], v[8:11]
	v_mfma_f32_16x16x32_bf16 v[4:7], v[156:159], v[206:209], v[4:7]
	v_mfma_f32_16x16x32_bf16 v[56:59], v[152:155], v[168:171], v[56:59]
	v_mfma_f32_16x16x32_bf16 v[52:55], v[160:163], v[168:171], v[52:55]
	v_mfma_f32_16x16x32_bf16 v[40:43], v[152:155], v[176:179], v[40:43]
	v_mfma_f32_16x16x32_bf16 v[36:39], v[160:163], v[176:179], v[36:39]
	v_mfma_f32_16x16x32_bf16 v[24:27], v[152:155], v[202:205], v[24:27]
	v_mfma_f32_16x16x32_bf16 v[20:23], v[160:163], v[202:205], v[20:23]
	v_mfma_f32_16x16x32_bf16 v[8:11], v[152:155], v[210:213], v[8:11]
	v_mfma_f32_16x16x32_bf16 v[4:7], v[160:163], v[210:213], v[4:7]
	s_setprio 0
	s_barrier
	s_cbranch_scc1 .LBB0_1025
	s_mov_b32 s0, s34
	s_branch .LBB0_1021

.LBB0_1096:
	v_add_u32_e32 v150, 0x10000, v136
	v_add_u32_e32 v166, 0x14000, v136
	ds_read_b128 v[138:141], v150
	ds_read_b128 v[142:145], v150 offset:1024
	ds_read_b128 v[146:149], v150 offset:2048
	ds_read_b128 v[150:153], v150 offset:3072
	ds_read_b128 v[154:157], v166
	ds_read_b128 v[158:161], v166 offset:1024
	ds_read_b128 v[162:165], v166 offset:2048
	ds_read_b128 v[166:169], v166 offset:3072
	s_add_i32 s71, s30, 2
	s_cmp_eq_u32 s60, s30
	s_cselect_b32 s40, s21, s67
	s_cselect_b32 s41, s3, s68
	s_cselect_b32 s38, s66, s69
	s_cselect_b32 s39, s65, s70
	s_add_u32 s30, s40, 0x80
	s_addc_u32 s31, s41, 0
	ds_read_b128 v[170:173], v137
	ds_read_b128 v[174:177], v137 offset:1024
	ds_read_b128 v[178:181], v137 offset:2048
	ds_read_b128 v[182:185], v137 offset:3072
	ds_read_b128 v[186:189], v137 offset:4096
	ds_read_b128 v[190:193], v137 offset:5120
	ds_read_b128 v[194:197], v137 offset:6144
	ds_read_b128 v[202:205], v137 offset:7168
	s_mov_b32 m0, s61
	s_nop 0
	global_load_lds_dwordx4 v1, s[28:29]
	s_mov_b32 m0, s62
	s_nop 0
	global_load_lds_dwordx4 v132, s[28:29]
	s_waitcnt vmcnt(8)
	s_waitcnt lgkmcnt(0)
	s_barrier
	s_setprio 1
	s_waitcnt lgkmcnt(7)
	v_mfma_f32_16x16x32_bf16 v[124:127], v[138:141], v[170:173], v[124:127]
	v_mfma_f32_16x16x32_bf16 v[128:131], v[146:149], v[170:173], v[128:131]
	s_waitcnt lgkmcnt(5)
	v_mfma_f32_16x16x32_bf16 v[112:115], v[138:141], v[178:181], v[112:115]
	v_mfma_f32_16x16x32_bf16 v[108:111], v[146:149], v[178:181], v[108:111]
	s_waitcnt lgkmcnt(3)
	v_mfma_f32_16x16x32_bf16 v[96:99], v[138:141], v[186:189], v[96:99]
	v_mfma_f32_16x16x32_bf16 v[92:95], v[146:149], v[186:189], v[92:95]
	s_waitcnt lgkmcnt(1)
	v_mfma_f32_16x16x32_bf16 v[80:83], v[138:141], v[194:197], v[80:83]
	v_mfma_f32_16x16x32_bf16 v[76:79], v[146:149], v[194:197], v[76:79]
	v_mfma_f32_16x16x32_bf16 v[124:127], v[142:145], v[174:177], v[124:127]
	v_mfma_f32_16x16x32_bf16 v[128:131], v[150:153], v[174:177], v[128:131]
	v_mfma_f32_16x16x32_bf16 v[112:115], v[142:145], v[182:185], v[112:115]
	v_mfma_f32_16x16x32_bf16 v[108:111], v[150:153], v[182:185], v[108:111]
	v_mfma_f32_16x16x32_bf16 v[96:99], v[142:145], v[190:193], v[96:99]
	v_mfma_f32_16x16x32_bf16 v[92:95], v[150:153], v[190:193], v[92:95]
	s_waitcnt lgkmcnt(0)
	v_mfma_f32_16x16x32_bf16 v[80:83], v[142:145], v[202:205], v[80:83]
	v_mfma_f32_16x16x32_bf16 v[76:79], v[150:153], v[202:205], v[76:79]
	s_setprio 0
	s_setprio 1
	v_mfma_f32_16x16x32_bf16 v[120:123], v[154:157], v[170:173], v[120:123]
	v_mfma_f32_16x16x32_bf16 v[116:119], v[162:165], v[170:173], v[116:119]
	v_mfma_f32_16x16x32_bf16 v[104:107], v[154:157], v[178:181], v[104:107]
	v_mfma_f32_16x16x32_bf16 v[100:103], v[162:165], v[178:181], v[100:103]
	v_mfma_f32_16x16x32_bf16 v[88:91], v[154:157], v[186:189], v[88:91]
	v_mfma_f32_16x16x32_bf16 v[84:87], v[162:165], v[186:189], v[84:87]
	v_mfma_f32_16x16x32_bf16 v[72:75], v[154:157], v[194:197], v[72:75]
	v_mfma_f32_16x16x32_bf16 v[68:71], v[162:165], v[194:197], v[68:71]
	v_mfma_f32_16x16x32_bf16 v[120:123], v[158:161], v[174:177], v[120:123]
	v_mfma_f32_16x16x32_bf16 v[116:119], v[166:169], v[174:177], v[116:119]
	v_mfma_f32_16x16x32_bf16 v[104:107], v[158:161], v[182:185], v[104:107]
	v_mfma_f32_16x16x32_bf16 v[100:103], v[166:169], v[182:185], v[100:103]
	v_mfma_f32_16x16x32_bf16 v[88:91], v[158:161], v[190:193], v[88:91]
	v_mfma_f32_16x16x32_bf16 v[84:87], v[166:169], v[190:193], v[84:87]
	v_mfma_f32_16x16x32_bf16 v[72:75], v[158:161], v[202:205], v[72:75]
	v_mfma_f32_16x16x32_bf16 v[68:71], v[166:169], v[202:205], v[68:71]
	s_setprio 0
	s_barrier
	ds_read_b128 v[170:173], v137 offset:16384
	ds_read_b128 v[174:177], v137 offset:17408
	ds_read_b128 v[178:181], v137 offset:18432
	ds_read_b128 v[182:185], v137 offset:19456
	ds_read_b128 v[186:189], v137 offset:20480
	ds_read_b128 v[190:193], v137 offset:21504
	ds_read_b128 v[194:197], v137 offset:22528
	ds_read_b128 v[202:205], v137 offset:23552
	s_mov_b32 m0, s23
	s_nop 0
	global_load_lds_dwordx4 v2, s[38:39]
	s_mov_b32 m0, s42
	s_nop 0
	global_load_lds_dwordx4 v133, s[38:39]
	s_add_u32 s72, s38, 0x80000
	s_addc_u32 s73, s39, 0
	s_mov_b32 m0, s43
	s_nop 0
	global_load_lds_dwordx4 v2, s[72:73]
	s_mov_b32 m0, s48
	s_nop 0
	global_load_lds_dwordx4 v133, s[72:73]
	s_mov_b32 m0, s35
	s_nop 0
	global_load_lds_dwordx4 v1, s[40:41]
	s_mov_b32 m0, s49
	s_nop 0
	global_load_lds_dwordx4 v132, s[40:41]
	s_waitcnt vmcnt(8)
	s_waitcnt lgkmcnt(0)
	s_barrier
	s_setprio 1
	s_waitcnt lgkmcnt(7)
	v_mfma_f32_16x16x32_bf16 v[64:67], v[138:141], v[170:173], v[64:67]
	v_mfma_f32_16x16x32_bf16 v[60:63], v[146:149], v[170:173], v[60:63]
	s_waitcnt lgkmcnt(5)
	v_mfma_f32_16x16x32_bf16 v[48:51], v[138:141], v[178:181], v[48:51]
	v_mfma_f32_16x16x32_bf16 v[44:47], v[146:149], v[178:181], v[44:47]
	s_waitcnt lgkmcnt(3)
	v_mfma_f32_16x16x32_bf16 v[32:35], v[138:141], v[186:189], v[32:35]
	v_mfma_f32_16x16x32_bf16 v[28:31], v[146:149], v[186:189], v[28:31]
	s_waitcnt lgkmcnt(1)
	v_mfma_f32_16x16x32_bf16 v[16:19], v[138:141], v[194:197], v[16:19]
	v_mfma_f32_16x16x32_bf16 v[12:15], v[146:149], v[194:197], v[12:15]
	v_mfma_f32_16x16x32_bf16 v[64:67], v[142:145], v[174:177], v[64:67]
	v_mfma_f32_16x16x32_bf16 v[60:63], v[150:153], v[174:177], v[60:63]
	v_mfma_f32_16x16x32_bf16 v[48:51], v[142:145], v[182:185], v[48:51]
	v_mfma_f32_16x16x32_bf16 v[44:47], v[150:153], v[182:185], v[44:47]
	v_mfma_f32_16x16x32_bf16 v[32:35], v[142:145], v[190:193], v[32:35]
	v_mfma_f32_16x16x32_bf16 v[28:31], v[150:153], v[190:193], v[28:31]
	s_waitcnt lgkmcnt(0)
	v_mfma_f32_16x16x32_bf16 v[16:19], v[142:145], v[202:205], v[16:19]
	v_mfma_f32_16x16x32_bf16 v[12:15], v[150:153], v[202:205], v[12:15]
	s_setprio 0
	s_setprio 1
	v_mfma_f32_16x16x32_bf16 v[56:59], v[154:157], v[170:173], v[56:59]
	v_mfma_f32_16x16x32_bf16 v[52:55], v[162:165], v[170:173], v[52:55]
	v_mfma_f32_16x16x32_bf16 v[40:43], v[154:157], v[178:181], v[40:43]
	v_mfma_f32_16x16x32_bf16 v[36:39], v[162:165], v[178:181], v[36:39]
	v_mfma_f32_16x16x32_bf16 v[24:27], v[154:157], v[186:189], v[24:27]
	v_mfma_f32_16x16x32_bf16 v[20:23], v[162:165], v[186:189], v[20:23]
	v_mfma_f32_16x16x32_bf16 v[8:11], v[154:157], v[194:197], v[8:11]
	v_mfma_f32_16x16x32_bf16 v[4:7], v[162:165], v[194:197], v[4:7]
	v_mfma_f32_16x16x32_bf16 v[56:59], v[158:161], v[174:177], v[56:59]
	v_mfma_f32_16x16x32_bf16 v[52:55], v[166:169], v[174:177], v[52:55]
	v_mfma_f32_16x16x32_bf16 v[40:43], v[158:161], v[182:185], v[40:43]
	v_mfma_f32_16x16x32_bf16 v[36:39], v[166:169], v[182:185], v[36:39]
	v_mfma_f32_16x16x32_bf16 v[24:27], v[158:161], v[190:193], v[24:27]
	v_mfma_f32_16x16x32_bf16 v[20:23], v[166:169], v[190:193], v[20:23]
	v_mfma_f32_16x16x32_bf16 v[8:11], v[158:161], v[202:205], v[8:11]
	v_mfma_f32_16x16x32_bf16 v[4:7], v[166:169], v[202:205], v[4:7]
	s_setprio 0
	s_barrier
	v_add_u32_e32 v150, 0x18000, v136
	v_add_u32_e32 v166, 0x1c000, v136
	ds_read_b128 v[138:141], v150
	ds_read_b128 v[142:145], v150 offset:1024
	ds_read_b128 v[146:149], v150 offset:2048
	ds_read_b128 v[150:153], v150 offset:3072
	ds_read_b128 v[154:157], v166
	ds_read_b128 v[158:161], v166 offset:1024
	ds_read_b128 v[162:165], v166 offset:2048
	ds_read_b128 v[166:169], v166 offset:3072
	ds_read_b128 v[170:173], v137 offset:32768
	ds_read_b128 v[174:177], v137 offset:33792
	ds_read_b128 v[178:181], v137 offset:34816
	ds_read_b128 v[182:185], v137 offset:35840
	ds_read_b128 v[186:189], v137 offset:36864
	ds_read_b128 v[190:193], v137 offset:37888
	ds_read_b128 v[194:197], v137 offset:38912
	ds_read_b128 v[202:205], v137 offset:39936
	s_add_u32 s40, s40, 0x80000
	s_addc_u32 s41, s41, 0
	s_mov_b32 m0, s50
	s_nop 0
	global_load_lds_dwordx4 v1, s[40:41]
	s_mov_b32 m0, s51
	s_nop 0
	global_load_lds_dwordx4 v132, s[40:41]
	s_waitcnt vmcnt(8)
	s_waitcnt lgkmcnt(0)
	s_barrier
	s_setprio 1
	s_waitcnt lgkmcnt(7)
	v_mfma_f32_16x16x32_bf16 v[124:127], v[138:141], v[170:173], v[124:127]
	v_mfma_f32_16x16x32_bf16 v[128:131], v[146:149], v[170:173], v[128:131]
	s_waitcnt lgkmcnt(5)
	v_mfma_f32_16x16x32_bf16 v[112:115], v[138:141], v[178:181], v[112:115]
	v_mfma_f32_16x16x32_bf16 v[108:111], v[146:149], v[178:181], v[108:111]
	s_waitcnt lgkmcnt(3)
	v_mfma_f32_16x16x32_bf16 v[96:99], v[138:141], v[186:189], v[96:99]
	v_mfma_f32_16x16x32_bf16 v[92:95], v[146:149], v[186:189], v[92:95]
	s_waitcnt lgkmcnt(1)
	v_mfma_f32_16x16x32_bf16 v[80:83], v[138:141], v[194:197], v[80:83]
	v_mfma_f32_16x16x32_bf16 v[76:79], v[146:149], v[194:197], v[76:79]
	v_mfma_f32_16x16x32_bf16 v[124:127], v[142:145], v[174:177], v[124:127]
	v_mfma_f32_16x16x32_bf16 v[128:131], v[150:153], v[174:177], v[128:131]
	v_mfma_f32_16x16x32_bf16 v[112:115], v[142:145], v[182:185], v[112:115]
	v_mfma_f32_16x16x32_bf16 v[108:111], v[150:153], v[182:185], v[108:111]
	v_mfma_f32_16x16x32_bf16 v[96:99], v[142:145], v[190:193], v[96:99]
	v_mfma_f32_16x16x32_bf16 v[92:95], v[150:153], v[190:193], v[92:95]
	s_waitcnt lgkmcnt(0)
	v_mfma_f32_16x16x32_bf16 v[80:83], v[142:145], v[202:205], v[80:83]
	v_mfma_f32_16x16x32_bf16 v[76:79], v[150:153], v[202:205], v[76:79]
	s_setprio 0
	s_setprio 1
	v_mfma_f32_16x16x32_bf16 v[120:123], v[154:157], v[170:173], v[120:123]
	v_mfma_f32_16x16x32_bf16 v[116:119], v[162:165], v[170:173], v[116:119]
	v_mfma_f32_16x16x32_bf16 v[104:107], v[154:157], v[178:181], v[104:107]
	v_mfma_f32_16x16x32_bf16 v[100:103], v[162:165], v[178:181], v[100:103]
	v_mfma_f32_16x16x32_bf16 v[88:91], v[154:157], v[186:189], v[88:91]
	v_mfma_f32_16x16x32_bf16 v[84:87], v[162:165], v[186:189], v[84:87]
	v_mfma_f32_16x16x32_bf16 v[72:75], v[154:157], v[194:197], v[72:75]
	v_mfma_f32_16x16x32_bf16 v[68:71], v[162:165], v[194:197], v[68:71]
	v_mfma_f32_16x16x32_bf16 v[120:123], v[158:161], v[174:177], v[120:123]
	v_mfma_f32_16x16x32_bf16 v[116:119], v[166:169], v[174:177], v[116:119]
	v_mfma_f32_16x16x32_bf16 v[104:107], v[158:161], v[182:185], v[104:107]
	v_mfma_f32_16x16x32_bf16 v[100:103], v[166:169], v[182:185], v[100:103]
	v_mfma_f32_16x16x32_bf16 v[88:91], v[158:161], v[190:193], v[88:91]
	v_mfma_f32_16x16x32_bf16 v[84:87], v[166:169], v[190:193], v[84:87]
	v_mfma_f32_16x16x32_bf16 v[72:75], v[158:161], v[202:205], v[72:75]
	v_mfma_f32_16x16x32_bf16 v[68:71], v[166:169], v[202:205], v[68:71]
	s_setprio 0
	s_barrier
	ds_read_b128 v[170:173], v137 offset:49152
	ds_read_b128 v[174:177], v137 offset:50176
	ds_read_b128 v[178:181], v137 offset:51200
	ds_read_b128 v[182:185], v137 offset:52224
	ds_read_b128 v[186:189], v137 offset:53248
	ds_read_b128 v[190:193], v137 offset:54272
	ds_read_b128 v[194:197], v137 offset:55296
	ds_read_b128 v[202:205], v137 offset:56320
	s_add_u32 s40, s38, 0x80
	s_addc_u32 s41, s39, 0
	s_mov_b32 m0, s54
	s_nop 0
	global_load_lds_dwordx4 v2, s[40:41]
	s_add_u32 s38, s38, 0x80080
	s_mov_b32 m0, s55
	s_nop 0
	global_load_lds_dwordx4 v133, s[40:41]
	s_addc_u32 s39, s39, 0
	s_mov_b32 m0, s58
	s_nop 0
	global_load_lds_dwordx4 v2, s[38:39]
	s_mov_b32 m0, s59
	s_nop 0
	global_load_lds_dwordx4 v133, s[38:39]
	s_mov_b32 m0, s56
	s_nop 0
	global_load_lds_dwordx4 v1, s[30:31]
	s_mov_b32 m0, s57
	s_nop 0
	global_load_lds_dwordx4 v132, s[30:31]
	s_waitcnt vmcnt(8)
	s_waitcnt lgkmcnt(0)
	s_barrier
	s_setprio 1
	s_waitcnt lgkmcnt(7)
	v_mfma_f32_16x16x32_bf16 v[64:67], v[138:141], v[170:173], v[64:67]
	v_mfma_f32_16x16x32_bf16 v[60:63], v[146:149], v[170:173], v[60:63]
	s_add_u32 s67, s67, 0x100
	s_waitcnt lgkmcnt(5)
	v_mfma_f32_16x16x32_bf16 v[48:51], v[138:141], v[178:181], v[48:51]
	s_addc_u32 s68, s68, 0
	v_mfma_f32_16x16x32_bf16 v[44:47], v[146:149], v[178:181], v[44:47]
	s_add_u32 s69, s69, 0x100
	s_waitcnt lgkmcnt(3)
	v_mfma_f32_16x16x32_bf16 v[32:35], v[138:141], v[186:189], v[32:35]
	s_addc_u32 s70, s70, 0
	v_mfma_f32_16x16x32_bf16 v[28:31], v[146:149], v[186:189], v[28:31]
	s_add_u32 s28, s28, 0x100
	s_waitcnt lgkmcnt(1)
	v_mfma_f32_16x16x32_bf16 v[16:19], v[138:141], v[194:197], v[16:19]
	s_addc_u32 s29, s29, 0
	v_mfma_f32_16x16x32_bf16 v[12:15], v[146:149], v[194:197], v[12:15]
	s_mov_b32 s30, s71
	v_mfma_f32_16x16x32_bf16 v[64:67], v[142:145], v[174:177], v[64:67]
	s_cmp_ge_i32 s71, s53
	v_mfma_f32_16x16x32_bf16 v[60:63], v[150:153], v[174:177], v[60:63]
	v_mfma_f32_16x16x32_bf16 v[48:51], v[142:145], v[182:185], v[48:51]
	v_mfma_f32_16x16x32_bf16 v[44:47], v[150:153], v[182:185], v[44:47]
	v_mfma_f32_16x16x32_bf16 v[32:35], v[142:145], v[190:193], v[32:35]
	v_mfma_f32_16x16x32_bf16 v[28:31], v[150:153], v[190:193], v[28:31]
	s_waitcnt lgkmcnt(0)
	v_mfma_f32_16x16x32_bf16 v[16:19], v[142:145], v[202:205], v[16:19]
	v_mfma_f32_16x16x32_bf16 v[12:15], v[150:153], v[202:205], v[12:15]
	s_setprio 0
	s_setprio 1
	v_mfma_f32_16x16x32_bf16 v[56:59], v[154:157], v[170:173], v[56:59]
	v_mfma_f32_16x16x32_bf16 v[52:55], v[162:165], v[170:173], v[52:55]
	v_mfma_f32_16x16x32_bf16 v[40:43], v[154:157], v[178:181], v[40:43]
	v_mfma_f32_16x16x32_bf16 v[36:39], v[162:165], v[178:181], v[36:39]
	v_mfma_f32_16x16x32_bf16 v[24:27], v[154:157], v[186:189], v[24:27]
	v_mfma_f32_16x16x32_bf16 v[20:23], v[162:165], v[186:189], v[20:23]
	v_mfma_f32_16x16x32_bf16 v[8:11], v[154:157], v[194:197], v[8:11]
	v_mfma_f32_16x16x32_bf16 v[4:7], v[162:165], v[194:197], v[4:7]
	v_mfma_f32_16x16x32_bf16 v[56:59], v[158:161], v[174:177], v[56:59]
	v_mfma_f32_16x16x32_bf16 v[52:55], v[166:169], v[174:177], v[52:55]
	v_mfma_f32_16x16x32_bf16 v[40:43], v[158:161], v[182:185], v[40:43]
	v_mfma_f32_16x16x32_bf16 v[36:39], v[166:169], v[182:185], v[36:39]
	v_mfma_f32_16x16x32_bf16 v[24:27], v[158:161], v[190:193], v[24:27]
	v_mfma_f32_16x16x32_bf16 v[20:23], v[166:169], v[190:193], v[20:23]
	v_mfma_f32_16x16x32_bf16 v[8:11], v[158:161], v[202:205], v[8:11]
	v_mfma_f32_16x16x32_bf16 v[4:7], v[166:169], v[202:205], v[4:7]
	s_setprio 0
	s_barrier
	s_cbranch_scc0 .LBB0_1096

.LBB0_1237:
	v_add_u32_e32 v132, 0x10000, v138
	ds_read_b128 v[140:143], v132
	ds_read_b128 v[144:147], v132 offset:1024
	ds_read_b128 v[148:151], v132 offset:2048
	ds_read_b128 v[152:155], v132 offset:3072
	v_add_u32_e32 v132, 0x14000, v138
	ds_read_b128 v[156:159], v132
	ds_read_b128 v[160:163], v132 offset:1024
	ds_read_b128 v[164:167], v132 offset:2048
	ds_read_b128 v[168:171], v132 offset:3072
	s_add_i32 s69, s28, 2
	s_cmp_eq_u32 s59, s28
	s_cselect_b32 s38, s23, s65
	s_cselect_b32 s39, s21, s66
	s_cselect_b32 s30, s64, s67
	s_cselect_b32 s31, s63, s68
	s_add_u32 s28, s38, 0x80
	s_addc_u32 s29, s39, 0
	ds_read_b128 v[172:175], v139
	ds_read_b128 v[176:179], v139 offset:1024
	ds_read_b128 v[180:183], v139 offset:2048
	ds_read_b128 v[184:187], v139 offset:3072
	ds_read_b128 v[188:191], v139 offset:4096
	ds_read_b128 v[192:195], v139 offset:5120
	ds_read_b128 v[196:199], v139 offset:6144
	ds_read_b128 v[202:205], v139 offset:7168
	s_add_u32 s70, s65, 0x7ff80
	s_addc_u32 s71, s66, 0
	s_mov_b32 m0, s60
	s_nop 0
	global_load_lds_dwordx4 v1, s[70:71]
	s_mov_b32 m0, s61
	s_nop 0
	global_load_lds_dwordx4 v134, s[70:71]
	s_waitcnt vmcnt(8)
	s_waitcnt lgkmcnt(0)
	s_barrier
	s_setprio 1
	s_waitcnt lgkmcnt(7)
	v_mfma_f32_16x16x32_bf16 v[124:127], v[140:143], v[172:175], v[124:127]
	v_mfma_f32_16x16x32_bf16 v[128:131], v[148:151], v[172:175], v[128:131]
	s_waitcnt lgkmcnt(5)
	v_mfma_f32_16x16x32_bf16 v[112:115], v[140:143], v[180:183], v[112:115]
	v_mfma_f32_16x16x32_bf16 v[108:111], v[148:151], v[180:183], v[108:111]
	s_waitcnt lgkmcnt(3)
	v_mfma_f32_16x16x32_bf16 v[96:99], v[140:143], v[188:191], v[96:99]
	v_mfma_f32_16x16x32_bf16 v[92:95], v[148:151], v[188:191], v[92:95]
	s_waitcnt lgkmcnt(1)
	v_mfma_f32_16x16x32_bf16 v[80:83], v[140:143], v[196:199], v[80:83]
	v_mfma_f32_16x16x32_bf16 v[76:79], v[148:151], v[196:199], v[76:79]
	v_mfma_f32_16x16x32_bf16 v[124:127], v[144:147], v[176:179], v[124:127]
	v_mfma_f32_16x16x32_bf16 v[128:131], v[152:155], v[176:179], v[128:131]
	v_mfma_f32_16x16x32_bf16 v[112:115], v[144:147], v[184:187], v[112:115]
	v_mfma_f32_16x16x32_bf16 v[108:111], v[152:155], v[184:187], v[108:111]
	v_mfma_f32_16x16x32_bf16 v[96:99], v[144:147], v[192:195], v[96:99]
	v_mfma_f32_16x16x32_bf16 v[92:95], v[152:155], v[192:195], v[92:95]
	s_waitcnt lgkmcnt(0)
	v_mfma_f32_16x16x32_bf16 v[80:83], v[144:147], v[202:205], v[80:83]
	v_mfma_f32_16x16x32_bf16 v[76:79], v[152:155], v[202:205], v[76:79]
	s_setprio 0
	s_setprio 1
	v_mfma_f32_16x16x32_bf16 v[120:123], v[156:159], v[172:175], v[120:123]
	v_mfma_f32_16x16x32_bf16 v[116:119], v[164:167], v[172:175], v[116:119]
	v_mfma_f32_16x16x32_bf16 v[104:107], v[156:159], v[180:183], v[104:107]
	v_mfma_f32_16x16x32_bf16 v[100:103], v[164:167], v[180:183], v[100:103]
	v_mfma_f32_16x16x32_bf16 v[88:91], v[156:159], v[188:191], v[88:91]
	v_mfma_f32_16x16x32_bf16 v[84:87], v[164:167], v[188:191], v[84:87]
	v_mfma_f32_16x16x32_bf16 v[72:75], v[156:159], v[196:199], v[72:75]
	v_mfma_f32_16x16x32_bf16 v[68:71], v[164:167], v[196:199], v[68:71]
	v_mfma_f32_16x16x32_bf16 v[120:123], v[160:163], v[176:179], v[120:123]
	v_mfma_f32_16x16x32_bf16 v[116:119], v[168:171], v[176:179], v[116:119]
	v_mfma_f32_16x16x32_bf16 v[104:107], v[160:163], v[184:187], v[104:107]
	v_mfma_f32_16x16x32_bf16 v[100:103], v[168:171], v[184:187], v[100:103]
	v_mfma_f32_16x16x32_bf16 v[88:91], v[160:163], v[192:195], v[88:91]
	v_mfma_f32_16x16x32_bf16 v[84:87], v[168:171], v[192:195], v[84:87]
	v_mfma_f32_16x16x32_bf16 v[72:75], v[160:163], v[202:205], v[72:75]
	v_mfma_f32_16x16x32_bf16 v[68:71], v[168:171], v[202:205], v[68:71]
	s_setprio 0
	s_barrier
	ds_read_b128 v[172:175], v139 offset:16384
	ds_read_b128 v[176:179], v139 offset:17408
	ds_read_b128 v[180:183], v139 offset:18432
	ds_read_b128 v[184:187], v139 offset:19456
	ds_read_b128 v[188:191], v139 offset:20480
	ds_read_b128 v[192:195], v139 offset:21504
	ds_read_b128 v[196:199], v139 offset:22528
	ds_read_b128 v[202:205], v139 offset:23552
	s_mov_b32 m0, s40
	s_nop 0
	global_load_lds_dwordx4 v2, s[30:31]
	s_mov_b32 m0, s41
	s_nop 0
	global_load_lds_dwordx4 v135, s[30:31]
	s_add_u32 s70, s30, 0x80000
	s_addc_u32 s71, s31, 0
	s_mov_b32 m0, s42
	s_nop 0
	global_load_lds_dwordx4 v2, s[70:71]
	s_mov_b32 m0, s43
	s_nop 0
	global_load_lds_dwordx4 v135, s[70:71]
	s_mov_b32 m0, s0
	s_nop 0
	global_load_lds_dwordx4 v1, s[38:39]
	s_mov_b32 m0, s48
	s_nop 0
	global_load_lds_dwordx4 v134, s[38:39]
	s_waitcnt vmcnt(8)
	s_waitcnt lgkmcnt(0)
	s_barrier
	s_setprio 1
	s_waitcnt lgkmcnt(7)
	v_mfma_f32_16x16x32_bf16 v[64:67], v[140:143], v[172:175], v[64:67]
	v_mfma_f32_16x16x32_bf16 v[60:63], v[148:151], v[172:175], v[60:63]
	s_waitcnt lgkmcnt(5)
	v_mfma_f32_16x16x32_bf16 v[48:51], v[140:143], v[180:183], v[48:51]
	v_mfma_f32_16x16x32_bf16 v[44:47], v[148:151], v[180:183], v[44:47]
	s_waitcnt lgkmcnt(3)
	v_mfma_f32_16x16x32_bf16 v[32:35], v[140:143], v[188:191], v[32:35]
	v_mfma_f32_16x16x32_bf16 v[28:31], v[148:151], v[188:191], v[28:31]
	s_waitcnt lgkmcnt(1)
	v_mfma_f32_16x16x32_bf16 v[16:19], v[140:143], v[196:199], v[16:19]
	v_mfma_f32_16x16x32_bf16 v[12:15], v[148:151], v[196:199], v[12:15]
	v_mfma_f32_16x16x32_bf16 v[64:67], v[144:147], v[176:179], v[64:67]
	v_mfma_f32_16x16x32_bf16 v[60:63], v[152:155], v[176:179], v[60:63]
	v_mfma_f32_16x16x32_bf16 v[48:51], v[144:147], v[184:187], v[48:51]
	v_mfma_f32_16x16x32_bf16 v[44:47], v[152:155], v[184:187], v[44:47]
	v_mfma_f32_16x16x32_bf16 v[32:35], v[144:147], v[192:195], v[32:35]
	v_mfma_f32_16x16x32_bf16 v[28:31], v[152:155], v[192:195], v[28:31]
	s_waitcnt lgkmcnt(0)
	v_mfma_f32_16x16x32_bf16 v[16:19], v[144:147], v[202:205], v[16:19]
	v_mfma_f32_16x16x32_bf16 v[12:15], v[152:155], v[202:205], v[12:15]
	s_setprio 0
	s_setprio 1
	v_mfma_f32_16x16x32_bf16 v[56:59], v[156:159], v[172:175], v[56:59]
	v_mfma_f32_16x16x32_bf16 v[52:55], v[164:167], v[172:175], v[52:55]
	v_mfma_f32_16x16x32_bf16 v[40:43], v[156:159], v[180:183], v[40:43]
	v_mfma_f32_16x16x32_bf16 v[36:39], v[164:167], v[180:183], v[36:39]
	v_mfma_f32_16x16x32_bf16 v[24:27], v[156:159], v[188:191], v[24:27]
	v_mfma_f32_16x16x32_bf16 v[20:23], v[164:167], v[188:191], v[20:23]
	v_mfma_f32_16x16x32_bf16 v[8:11], v[156:159], v[196:199], v[8:11]
	v_mfma_f32_16x16x32_bf16 v[4:7], v[164:167], v[196:199], v[4:7]
	v_mfma_f32_16x16x32_bf16 v[56:59], v[160:163], v[176:179], v[56:59]
	v_mfma_f32_16x16x32_bf16 v[52:55], v[168:171], v[176:179], v[52:55]
	v_mfma_f32_16x16x32_bf16 v[40:43], v[160:163], v[184:187], v[40:43]
	v_mfma_f32_16x16x32_bf16 v[36:39], v[168:171], v[184:187], v[36:39]
	v_mfma_f32_16x16x32_bf16 v[24:27], v[160:163], v[192:195], v[24:27]
	v_mfma_f32_16x16x32_bf16 v[20:23], v[168:171], v[192:195], v[20:23]
	v_mfma_f32_16x16x32_bf16 v[8:11], v[160:163], v[202:205], v[8:11]
	v_mfma_f32_16x16x32_bf16 v[4:7], v[168:171], v[202:205], v[4:7]
	s_setprio 0
	s_barrier
	v_add_u32_e32 v132, 0x18000, v138
	ds_read_b128 v[140:143], v132
	ds_read_b128 v[144:147], v132 offset:1024
	ds_read_b128 v[148:151], v132 offset:2048
	ds_read_b128 v[152:155], v132 offset:3072
	v_add_u32_e32 v132, 0x1c000, v138
	ds_read_b128 v[156:159], v132
	ds_read_b128 v[160:163], v132 offset:1024
	ds_read_b128 v[164:167], v132 offset:2048
	ds_read_b128 v[168:171], v132 offset:3072
	ds_read_b128 v[172:175], v139 offset:32768
	ds_read_b128 v[176:179], v139 offset:33792
	ds_read_b128 v[180:183], v139 offset:34816
	ds_read_b128 v[184:187], v139 offset:35840
	ds_read_b128 v[188:191], v139 offset:36864
	ds_read_b128 v[192:195], v139 offset:37888
	ds_read_b128 v[196:199], v139 offset:38912
	ds_read_b128 v[202:205], v139 offset:39936
	s_add_u32 s38, s38, 0x80000
	s_addc_u32 s39, s39, 0
	s_mov_b32 m0, s49
	s_nop 0
	global_load_lds_dwordx4 v1, s[38:39]
	s_mov_b32 m0, s50
	s_nop 0
	global_load_lds_dwordx4 v134, s[38:39]
	s_waitcnt vmcnt(8)
	s_waitcnt lgkmcnt(0)
	s_barrier
	s_setprio 1
	s_waitcnt lgkmcnt(7)
	v_mfma_f32_16x16x32_bf16 v[124:127], v[140:143], v[172:175], v[124:127]
	v_mfma_f32_16x16x32_bf16 v[128:131], v[148:151], v[172:175], v[128:131]
	s_waitcnt lgkmcnt(5)
	v_mfma_f32_16x16x32_bf16 v[112:115], v[140:143], v[180:183], v[112:115]
	v_mfma_f32_16x16x32_bf16 v[108:111], v[148:151], v[180:183], v[108:111]
	s_waitcnt lgkmcnt(3)
	v_mfma_f32_16x16x32_bf16 v[96:99], v[140:143], v[188:191], v[96:99]
	v_mfma_f32_16x16x32_bf16 v[92:95], v[148:151], v[188:191], v[92:95]
	s_waitcnt lgkmcnt(1)
	v_mfma_f32_16x16x32_bf16 v[80:83], v[140:143], v[196:199], v[80:83]
	v_mfma_f32_16x16x32_bf16 v[76:79], v[148:151], v[196:199], v[76:79]
	v_mfma_f32_16x16x32_bf16 v[124:127], v[144:147], v[176:179], v[124:127]
	v_mfma_f32_16x16x32_bf16 v[128:131], v[152:155], v[176:179], v[128:131]
	v_mfma_f32_16x16x32_bf16 v[112:115], v[144:147], v[184:187], v[112:115]
	v_mfma_f32_16x16x32_bf16 v[108:111], v[152:155], v[184:187], v[108:111]
	v_mfma_f32_16x16x32_bf16 v[96:99], v[144:147], v[192:195], v[96:99]
	v_mfma_f32_16x16x32_bf16 v[92:95], v[152:155], v[192:195], v[92:95]
	s_waitcnt lgkmcnt(0)
	v_mfma_f32_16x16x32_bf16 v[80:83], v[144:147], v[202:205], v[80:83]
	v_mfma_f32_16x16x32_bf16 v[76:79], v[152:155], v[202:205], v[76:79]
	s_setprio 0
	s_setprio 1
	v_mfma_f32_16x16x32_bf16 v[120:123], v[156:159], v[172:175], v[120:123]
	v_mfma_f32_16x16x32_bf16 v[116:119], v[164:167], v[172:175], v[116:119]
	v_mfma_f32_16x16x32_bf16 v[104:107], v[156:159], v[180:183], v[104:107]
	v_mfma_f32_16x16x32_bf16 v[100:103], v[164:167], v[180:183], v[100:103]
	v_mfma_f32_16x16x32_bf16 v[88:91], v[156:159], v[188:191], v[88:91]
	v_mfma_f32_16x16x32_bf16 v[84:87], v[164:167], v[188:191], v[84:87]
	v_mfma_f32_16x16x32_bf16 v[72:75], v[156:159], v[196:199], v[72:75]
	v_mfma_f32_16x16x32_bf16 v[68:71], v[164:167], v[196:199], v[68:71]
	v_mfma_f32_16x16x32_bf16 v[120:123], v[160:163], v[176:179], v[120:123]
	v_mfma_f32_16x16x32_bf16 v[116:119], v[168:171], v[176:179], v[116:119]
	v_mfma_f32_16x16x32_bf16 v[104:107], v[160:163], v[184:187], v[104:107]
	v_mfma_f32_16x16x32_bf16 v[100:103], v[168:171], v[184:187], v[100:103]
	v_mfma_f32_16x16x32_bf16 v[88:91], v[160:163], v[192:195], v[88:91]
	v_mfma_f32_16x16x32_bf16 v[84:87], v[168:171], v[192:195], v[84:87]
	v_mfma_f32_16x16x32_bf16 v[72:75], v[160:163], v[202:205], v[72:75]
	v_mfma_f32_16x16x32_bf16 v[68:71], v[168:171], v[202:205], v[68:71]
	s_setprio 0
	s_barrier
	ds_read_b128 v[172:175], v139 offset:49152
	ds_read_b128 v[176:179], v139 offset:50176
	ds_read_b128 v[180:183], v139 offset:51200
	ds_read_b128 v[184:187], v139 offset:52224
	ds_read_b128 v[188:191], v139 offset:53248
	ds_read_b128 v[192:195], v139 offset:54272
	ds_read_b128 v[196:199], v139 offset:55296
	ds_read_b128 v[202:205], v139 offset:56320
	s_add_u32 s38, s30, 0x80
	s_addc_u32 s39, s31, 0
	s_mov_b32 m0, s53
	s_nop 0
	global_load_lds_dwordx4 v2, s[38:39]
	s_add_u32 s30, s30, 0x80080
	s_mov_b32 m0, s54
	s_nop 0
	global_load_lds_dwordx4 v135, s[38:39]
	s_addc_u32 s31, s31, 0
	s_mov_b32 m0, s57
	s_nop 0
	global_load_lds_dwordx4 v2, s[30:31]
	s_mov_b32 m0, s58
	s_nop 0
	global_load_lds_dwordx4 v135, s[30:31]
	s_mov_b32 m0, s55
	s_nop 0
	global_load_lds_dwordx4 v1, s[28:29]
	s_mov_b32 m0, s56
	s_nop 0
	global_load_lds_dwordx4 v134, s[28:29]
	s_waitcnt vmcnt(8)
	s_waitcnt lgkmcnt(0)
	s_barrier
	s_setprio 1
	s_waitcnt lgkmcnt(7)
	v_mfma_f32_16x16x32_bf16 v[64:67], v[140:143], v[172:175], v[64:67]
	v_mfma_f32_16x16x32_bf16 v[60:63], v[148:151], v[172:175], v[60:63]
	s_add_u32 s65, s65, 0x100
	s_waitcnt lgkmcnt(5)
	v_mfma_f32_16x16x32_bf16 v[48:51], v[140:143], v[180:183], v[48:51]
	s_addc_u32 s66, s66, 0
	v_mfma_f32_16x16x32_bf16 v[44:47], v[148:151], v[180:183], v[44:47]
	s_add_u32 s67, s67, 0x100
	s_waitcnt lgkmcnt(3)
	v_mfma_f32_16x16x32_bf16 v[32:35], v[140:143], v[188:191], v[32:35]
	s_addc_u32 s68, s68, 0
	v_mfma_f32_16x16x32_bf16 v[28:31], v[148:151], v[188:191], v[28:31]
	s_mov_b32 s28, s69
	s_waitcnt lgkmcnt(1)
	v_mfma_f32_16x16x32_bf16 v[16:19], v[140:143], v[196:199], v[16:19]
	s_cmp_ge_i32 s69, s52
	v_mfma_f32_16x16x32_bf16 v[12:15], v[148:151], v[196:199], v[12:15]
	v_mfma_f32_16x16x32_bf16 v[64:67], v[144:147], v[176:179], v[64:67]
	v_mfma_f32_16x16x32_bf16 v[60:63], v[152:155], v[176:179], v[60:63]
	v_mfma_f32_16x16x32_bf16 v[48:51], v[144:147], v[184:187], v[48:51]
	v_mfma_f32_16x16x32_bf16 v[44:47], v[152:155], v[184:187], v[44:47]
	v_mfma_f32_16x16x32_bf16 v[32:35], v[144:147], v[192:195], v[32:35]
	v_mfma_f32_16x16x32_bf16 v[28:31], v[152:155], v[192:195], v[28:31]
	s_waitcnt lgkmcnt(0)
	v_mfma_f32_16x16x32_bf16 v[16:19], v[144:147], v[202:205], v[16:19]
	v_mfma_f32_16x16x32_bf16 v[12:15], v[152:155], v[202:205], v[12:15]
	s_setprio 0
	s_setprio 1
	v_mfma_f32_16x16x32_bf16 v[56:59], v[156:159], v[172:175], v[56:59]
	v_mfma_f32_16x16x32_bf16 v[52:55], v[164:167], v[172:175], v[52:55]
	v_mfma_f32_16x16x32_bf16 v[40:43], v[156:159], v[180:183], v[40:43]
	v_mfma_f32_16x16x32_bf16 v[36:39], v[164:167], v[180:183], v[36:39]
	v_mfma_f32_16x16x32_bf16 v[24:27], v[156:159], v[188:191], v[24:27]
	v_mfma_f32_16x16x32_bf16 v[20:23], v[164:167], v[188:191], v[20:23]
	v_mfma_f32_16x16x32_bf16 v[8:11], v[156:159], v[196:199], v[8:11]
	v_mfma_f32_16x16x32_bf16 v[4:7], v[164:167], v[196:199], v[4:7]
	v_mfma_f32_16x16x32_bf16 v[56:59], v[160:163], v[176:179], v[56:59]
	v_mfma_f32_16x16x32_bf16 v[52:55], v[168:171], v[176:179], v[52:55]
	v_mfma_f32_16x16x32_bf16 v[40:43], v[160:163], v[184:187], v[40:43]
	v_mfma_f32_16x16x32_bf16 v[36:39], v[168:171], v[184:187], v[36:39]
	v_mfma_f32_16x16x32_bf16 v[24:27], v[160:163], v[192:195], v[24:27]
	v_mfma_f32_16x16x32_bf16 v[20:23], v[168:171], v[192:195], v[20:23]
	v_mfma_f32_16x16x32_bf16 v[8:11], v[160:163], v[202:205], v[8:11]
	v_mfma_f32_16x16x32_bf16 v[4:7], v[168:171], v[202:205], v[4:7]
	s_setprio 0
	s_barrier
	s_cbranch_scc0 .LBB0_1237

.LBB0_1309:
	v_add_u32_e32 v150, 0x10000, v136
	v_add_u32_e32 v166, 0x14000, v136
	ds_read_b128 v[138:141], v150
	ds_read_b128 v[142:145], v150 offset:1024
	ds_read_b128 v[146:149], v150 offset:2048
	ds_read_b128 v[150:153], v150 offset:3072
	ds_read_b128 v[154:157], v166
	ds_read_b128 v[158:161], v166 offset:1024
	ds_read_b128 v[162:165], v166 offset:2048
	ds_read_b128 v[166:169], v166 offset:3072
	s_add_i32 s71, s30, 2
	s_cmp_eq_u32 s60, s30
	s_cselect_b32 s40, s21, s67
	s_cselect_b32 s41, s3, s68
	s_cselect_b32 s38, s66, s69
	s_cselect_b32 s39, s65, s70
	s_add_u32 s30, s40, 0x80
	s_addc_u32 s31, s41, 0
	ds_read_b128 v[170:173], v137
	ds_read_b128 v[174:177], v137 offset:1024
	ds_read_b128 v[178:181], v137 offset:2048
	ds_read_b128 v[182:185], v137 offset:3072
	ds_read_b128 v[186:189], v137 offset:4096
	ds_read_b128 v[190:193], v137 offset:5120
	ds_read_b128 v[194:197], v137 offset:6144
	ds_read_b128 v[202:205], v137 offset:7168
	s_mov_b32 m0, s61
	s_nop 0
	global_load_lds_dwordx4 v1, s[28:29]
	s_mov_b32 m0, s62
	s_nop 0
	global_load_lds_dwordx4 v132, s[28:29]
	s_waitcnt vmcnt(8)
	s_waitcnt lgkmcnt(0)
	s_barrier
	s_setprio 1
	s_waitcnt lgkmcnt(7)
	v_mfma_f32_16x16x32_bf16 v[124:127], v[138:141], v[170:173], v[124:127]
	v_mfma_f32_16x16x32_bf16 v[128:131], v[146:149], v[170:173], v[128:131]
	s_waitcnt lgkmcnt(5)
	v_mfma_f32_16x16x32_bf16 v[112:115], v[138:141], v[178:181], v[112:115]
	v_mfma_f32_16x16x32_bf16 v[108:111], v[146:149], v[178:181], v[108:111]
	s_waitcnt lgkmcnt(3)
	v_mfma_f32_16x16x32_bf16 v[96:99], v[138:141], v[186:189], v[96:99]
	v_mfma_f32_16x16x32_bf16 v[92:95], v[146:149], v[186:189], v[92:95]
	s_waitcnt lgkmcnt(1)
	v_mfma_f32_16x16x32_bf16 v[80:83], v[138:141], v[194:197], v[80:83]
	v_mfma_f32_16x16x32_bf16 v[76:79], v[146:149], v[194:197], v[76:79]
	v_mfma_f32_16x16x32_bf16 v[124:127], v[142:145], v[174:177], v[124:127]
	v_mfma_f32_16x16x32_bf16 v[128:131], v[150:153], v[174:177], v[128:131]
	v_mfma_f32_16x16x32_bf16 v[112:115], v[142:145], v[182:185], v[112:115]
	v_mfma_f32_16x16x32_bf16 v[108:111], v[150:153], v[182:185], v[108:111]
	v_mfma_f32_16x16x32_bf16 v[96:99], v[142:145], v[190:193], v[96:99]
	v_mfma_f32_16x16x32_bf16 v[92:95], v[150:153], v[190:193], v[92:95]
	s_waitcnt lgkmcnt(0)
	v_mfma_f32_16x16x32_bf16 v[80:83], v[142:145], v[202:205], v[80:83]
	v_mfma_f32_16x16x32_bf16 v[76:79], v[150:153], v[202:205], v[76:79]
	s_setprio 0
	s_setprio 1
	v_mfma_f32_16x16x32_bf16 v[120:123], v[154:157], v[170:173], v[120:123]
	v_mfma_f32_16x16x32_bf16 v[116:119], v[162:165], v[170:173], v[116:119]
	v_mfma_f32_16x16x32_bf16 v[104:107], v[154:157], v[178:181], v[104:107]
	v_mfma_f32_16x16x32_bf16 v[100:103], v[162:165], v[178:181], v[100:103]
	v_mfma_f32_16x16x32_bf16 v[88:91], v[154:157], v[186:189], v[88:91]
	v_mfma_f32_16x16x32_bf16 v[84:87], v[162:165], v[186:189], v[84:87]
	v_mfma_f32_16x16x32_bf16 v[72:75], v[154:157], v[194:197], v[72:75]
	v_mfma_f32_16x16x32_bf16 v[68:71], v[162:165], v[194:197], v[68:71]
	v_mfma_f32_16x16x32_bf16 v[120:123], v[158:161], v[174:177], v[120:123]
	v_mfma_f32_16x16x32_bf16 v[116:119], v[166:169], v[174:177], v[116:119]
	v_mfma_f32_16x16x32_bf16 v[104:107], v[158:161], v[182:185], v[104:107]
	v_mfma_f32_16x16x32_bf16 v[100:103], v[166:169], v[182:185], v[100:103]
	v_mfma_f32_16x16x32_bf16 v[88:91], v[158:161], v[190:193], v[88:91]
	v_mfma_f32_16x16x32_bf16 v[84:87], v[166:169], v[190:193], v[84:87]
	v_mfma_f32_16x16x32_bf16 v[72:75], v[158:161], v[202:205], v[72:75]
	v_mfma_f32_16x16x32_bf16 v[68:71], v[166:169], v[202:205], v[68:71]
	s_setprio 0
	s_barrier
	ds_read_b128 v[170:173], v137 offset:16384
	ds_read_b128 v[174:177], v137 offset:17408
	ds_read_b128 v[178:181], v137 offset:18432
	ds_read_b128 v[182:185], v137 offset:19456
	ds_read_b128 v[186:189], v137 offset:20480
	ds_read_b128 v[190:193], v137 offset:21504
	ds_read_b128 v[194:197], v137 offset:22528
	ds_read_b128 v[202:205], v137 offset:23552
	s_mov_b32 m0, s23
	s_nop 0
	global_load_lds_dwordx4 v2, s[38:39]
	s_mov_b32 m0, s42
	s_nop 0
	global_load_lds_dwordx4 v133, s[38:39]
	s_add_u32 s72, s38, 0x200000
	s_addc_u32 s73, s39, 0
	s_mov_b32 m0, s43
	s_nop 0
	global_load_lds_dwordx4 v2, s[72:73]
	s_mov_b32 m0, s48
	s_nop 0
	global_load_lds_dwordx4 v133, s[72:73]
	s_mov_b32 m0, s35
	s_nop 0
	global_load_lds_dwordx4 v1, s[40:41]
	s_mov_b32 m0, s49
	s_nop 0
	global_load_lds_dwordx4 v132, s[40:41]
	s_waitcnt vmcnt(8)
	s_waitcnt lgkmcnt(0)
	s_barrier
	s_setprio 1
	s_waitcnt lgkmcnt(7)
	v_mfma_f32_16x16x32_bf16 v[64:67], v[138:141], v[170:173], v[64:67]
	v_mfma_f32_16x16x32_bf16 v[60:63], v[146:149], v[170:173], v[60:63]
	s_waitcnt lgkmcnt(5)
	v_mfma_f32_16x16x32_bf16 v[48:51], v[138:141], v[178:181], v[48:51]
	v_mfma_f32_16x16x32_bf16 v[44:47], v[146:149], v[178:181], v[44:47]
	s_waitcnt lgkmcnt(3)
	v_mfma_f32_16x16x32_bf16 v[32:35], v[138:141], v[186:189], v[32:35]
	v_mfma_f32_16x16x32_bf16 v[28:31], v[146:149], v[186:189], v[28:31]
	s_waitcnt lgkmcnt(1)
	v_mfma_f32_16x16x32_bf16 v[16:19], v[138:141], v[194:197], v[16:19]
	v_mfma_f32_16x16x32_bf16 v[12:15], v[146:149], v[194:197], v[12:15]
	v_mfma_f32_16x16x32_bf16 v[64:67], v[142:145], v[174:177], v[64:67]
	v_mfma_f32_16x16x32_bf16 v[60:63], v[150:153], v[174:177], v[60:63]
	v_mfma_f32_16x16x32_bf16 v[48:51], v[142:145], v[182:185], v[48:51]
	v_mfma_f32_16x16x32_bf16 v[44:47], v[150:153], v[182:185], v[44:47]
	v_mfma_f32_16x16x32_bf16 v[32:35], v[142:145], v[190:193], v[32:35]
	v_mfma_f32_16x16x32_bf16 v[28:31], v[150:153], v[190:193], v[28:31]
	s_waitcnt lgkmcnt(0)
	v_mfma_f32_16x16x32_bf16 v[16:19], v[142:145], v[202:205], v[16:19]
	v_mfma_f32_16x16x32_bf16 v[12:15], v[150:153], v[202:205], v[12:15]
	s_setprio 0
	s_setprio 1
	v_mfma_f32_16x16x32_bf16 v[56:59], v[154:157], v[170:173], v[56:59]
	v_mfma_f32_16x16x32_bf16 v[52:55], v[162:165], v[170:173], v[52:55]
	v_mfma_f32_16x16x32_bf16 v[40:43], v[154:157], v[178:181], v[40:43]
	v_mfma_f32_16x16x32_bf16 v[36:39], v[162:165], v[178:181], v[36:39]
	v_mfma_f32_16x16x32_bf16 v[24:27], v[154:157], v[186:189], v[24:27]
	v_mfma_f32_16x16x32_bf16 v[20:23], v[162:165], v[186:189], v[20:23]
	v_mfma_f32_16x16x32_bf16 v[8:11], v[154:157], v[194:197], v[8:11]
	v_mfma_f32_16x16x32_bf16 v[4:7], v[162:165], v[194:197], v[4:7]
	v_mfma_f32_16x16x32_bf16 v[56:59], v[158:161], v[174:177], v[56:59]
	v_mfma_f32_16x16x32_bf16 v[52:55], v[166:169], v[174:177], v[52:55]
	v_mfma_f32_16x16x32_bf16 v[40:43], v[158:161], v[182:185], v[40:43]
	v_mfma_f32_16x16x32_bf16 v[36:39], v[166:169], v[182:185], v[36:39]
	v_mfma_f32_16x16x32_bf16 v[24:27], v[158:161], v[190:193], v[24:27]
	v_mfma_f32_16x16x32_bf16 v[20:23], v[166:169], v[190:193], v[20:23]
	v_mfma_f32_16x16x32_bf16 v[8:11], v[158:161], v[202:205], v[8:11]
	v_mfma_f32_16x16x32_bf16 v[4:7], v[166:169], v[202:205], v[4:7]
	s_setprio 0
	s_barrier
	v_add_u32_e32 v150, 0x18000, v136
	v_add_u32_e32 v166, 0x1c000, v136
	ds_read_b128 v[138:141], v150
	ds_read_b128 v[142:145], v150 offset:1024
	ds_read_b128 v[146:149], v150 offset:2048
	ds_read_b128 v[150:153], v150 offset:3072
	ds_read_b128 v[154:157], v166
	ds_read_b128 v[158:161], v166 offset:1024
	ds_read_b128 v[162:165], v166 offset:2048
	ds_read_b128 v[166:169], v166 offset:3072
	ds_read_b128 v[170:173], v137 offset:32768
	ds_read_b128 v[174:177], v137 offset:33792
	ds_read_b128 v[178:181], v137 offset:34816
	ds_read_b128 v[182:185], v137 offset:35840
	ds_read_b128 v[186:189], v137 offset:36864
	ds_read_b128 v[190:193], v137 offset:37888
	ds_read_b128 v[194:197], v137 offset:38912
	ds_read_b128 v[202:205], v137 offset:39936
	s_add_u32 s40, s40, 0x200000
	s_addc_u32 s41, s41, 0
	s_mov_b32 m0, s50
	s_nop 0
	global_load_lds_dwordx4 v1, s[40:41]
	s_mov_b32 m0, s51
	s_nop 0
	global_load_lds_dwordx4 v132, s[40:41]
	s_waitcnt vmcnt(8)
	s_waitcnt lgkmcnt(0)
	s_barrier
	s_setprio 1
	s_waitcnt lgkmcnt(7)
	v_mfma_f32_16x16x32_bf16 v[124:127], v[138:141], v[170:173], v[124:127]
	v_mfma_f32_16x16x32_bf16 v[128:131], v[146:149], v[170:173], v[128:131]
	s_waitcnt lgkmcnt(5)
	v_mfma_f32_16x16x32_bf16 v[112:115], v[138:141], v[178:181], v[112:115]
	v_mfma_f32_16x16x32_bf16 v[108:111], v[146:149], v[178:181], v[108:111]
	s_waitcnt lgkmcnt(3)
	v_mfma_f32_16x16x32_bf16 v[96:99], v[138:141], v[186:189], v[96:99]
	v_mfma_f32_16x16x32_bf16 v[92:95], v[146:149], v[186:189], v[92:95]
	s_waitcnt lgkmcnt(1)
	v_mfma_f32_16x16x32_bf16 v[80:83], v[138:141], v[194:197], v[80:83]
	v_mfma_f32_16x16x32_bf16 v[76:79], v[146:149], v[194:197], v[76:79]
	v_mfma_f32_16x16x32_bf16 v[124:127], v[142:145], v[174:177], v[124:127]
	v_mfma_f32_16x16x32_bf16 v[128:131], v[150:153], v[174:177], v[128:131]
	v_mfma_f32_16x16x32_bf16 v[112:115], v[142:145], v[182:185], v[112:115]
	v_mfma_f32_16x16x32_bf16 v[108:111], v[150:153], v[182:185], v[108:111]
	v_mfma_f32_16x16x32_bf16 v[96:99], v[142:145], v[190:193], v[96:99]
	v_mfma_f32_16x16x32_bf16 v[92:95], v[150:153], v[190:193], v[92:95]
	s_waitcnt lgkmcnt(0)
	v_mfma_f32_16x16x32_bf16 v[80:83], v[142:145], v[202:205], v[80:83]
	v_mfma_f32_16x16x32_bf16 v[76:79], v[150:153], v[202:205], v[76:79]
	s_setprio 0
	s_setprio 1
	v_mfma_f32_16x16x32_bf16 v[120:123], v[154:157], v[170:173], v[120:123]
	v_mfma_f32_16x16x32_bf16 v[116:119], v[162:165], v[170:173], v[116:119]
	v_mfma_f32_16x16x32_bf16 v[104:107], v[154:157], v[178:181], v[104:107]
	v_mfma_f32_16x16x32_bf16 v[100:103], v[162:165], v[178:181], v[100:103]
	v_mfma_f32_16x16x32_bf16 v[88:91], v[154:157], v[186:189], v[88:91]
	v_mfma_f32_16x16x32_bf16 v[84:87], v[162:165], v[186:189], v[84:87]
	v_mfma_f32_16x16x32_bf16 v[72:75], v[154:157], v[194:197], v[72:75]
	v_mfma_f32_16x16x32_bf16 v[68:71], v[162:165], v[194:197], v[68:71]
	v_mfma_f32_16x16x32_bf16 v[120:123], v[158:161], v[174:177], v[120:123]
	v_mfma_f32_16x16x32_bf16 v[116:119], v[166:169], v[174:177], v[116:119]
	v_mfma_f32_16x16x32_bf16 v[104:107], v[158:161], v[182:185], v[104:107]
	v_mfma_f32_16x16x32_bf16 v[100:103], v[166:169], v[182:185], v[100:103]
	v_mfma_f32_16x16x32_bf16 v[88:91], v[158:161], v[190:193], v[88:91]
	v_mfma_f32_16x16x32_bf16 v[84:87], v[166:169], v[190:193], v[84:87]
	v_mfma_f32_16x16x32_bf16 v[72:75], v[158:161], v[202:205], v[72:75]
	v_mfma_f32_16x16x32_bf16 v[68:71], v[166:169], v[202:205], v[68:71]
	s_setprio 0
	s_barrier
	ds_read_b128 v[170:173], v137 offset:49152
	ds_read_b128 v[174:177], v137 offset:50176
	ds_read_b128 v[178:181], v137 offset:51200
	ds_read_b128 v[182:185], v137 offset:52224
	ds_read_b128 v[186:189], v137 offset:53248
	ds_read_b128 v[190:193], v137 offset:54272
	ds_read_b128 v[194:197], v137 offset:55296
	ds_read_b128 v[202:205], v137 offset:56320
	s_add_u32 s40, s38, 0x80
	s_addc_u32 s41, s39, 0
	s_mov_b32 m0, s54
	s_nop 0
	global_load_lds_dwordx4 v2, s[40:41]
	s_add_u32 s38, s38, 0x200080
	s_mov_b32 m0, s55
	s_nop 0
	global_load_lds_dwordx4 v133, s[40:41]
	s_addc_u32 s39, s39, 0
	s_mov_b32 m0, s58
	s_nop 0
	global_load_lds_dwordx4 v2, s[38:39]
	s_mov_b32 m0, s59
	s_nop 0
	global_load_lds_dwordx4 v133, s[38:39]
	s_mov_b32 m0, s56
	s_nop 0
	global_load_lds_dwordx4 v1, s[30:31]
	s_mov_b32 m0, s57
	s_nop 0
	global_load_lds_dwordx4 v132, s[30:31]
	s_waitcnt vmcnt(8)
	s_waitcnt lgkmcnt(0)
	s_barrier
	s_setprio 1
	s_waitcnt lgkmcnt(7)
	v_mfma_f32_16x16x32_bf16 v[64:67], v[138:141], v[170:173], v[64:67]
	v_mfma_f32_16x16x32_bf16 v[60:63], v[146:149], v[170:173], v[60:63]
	s_add_u32 s67, s67, 0x100
	s_waitcnt lgkmcnt(5)
	v_mfma_f32_16x16x32_bf16 v[48:51], v[138:141], v[178:181], v[48:51]
	s_addc_u32 s68, s68, 0
	v_mfma_f32_16x16x32_bf16 v[44:47], v[146:149], v[178:181], v[44:47]
	s_add_u32 s69, s69, 0x100
	s_waitcnt lgkmcnt(3)
	v_mfma_f32_16x16x32_bf16 v[32:35], v[138:141], v[186:189], v[32:35]
	s_addc_u32 s70, s70, 0
	v_mfma_f32_16x16x32_bf16 v[28:31], v[146:149], v[186:189], v[28:31]
	s_add_u32 s28, s28, 0x100
	s_waitcnt lgkmcnt(1)
	v_mfma_f32_16x16x32_bf16 v[16:19], v[138:141], v[194:197], v[16:19]
	s_addc_u32 s29, s29, 0
	v_mfma_f32_16x16x32_bf16 v[12:15], v[146:149], v[194:197], v[12:15]
	s_mov_b32 s30, s71
	v_mfma_f32_16x16x32_bf16 v[64:67], v[142:145], v[174:177], v[64:67]
	s_cmp_ge_i32 s71, s53
	v_mfma_f32_16x16x32_bf16 v[60:63], v[150:153], v[174:177], v[60:63]
	v_mfma_f32_16x16x32_bf16 v[48:51], v[142:145], v[182:185], v[48:51]
	v_mfma_f32_16x16x32_bf16 v[44:47], v[150:153], v[182:185], v[44:47]
	v_mfma_f32_16x16x32_bf16 v[32:35], v[142:145], v[190:193], v[32:35]
	v_mfma_f32_16x16x32_bf16 v[28:31], v[150:153], v[190:193], v[28:31]
	s_waitcnt lgkmcnt(0)
	v_mfma_f32_16x16x32_bf16 v[16:19], v[142:145], v[202:205], v[16:19]
	v_mfma_f32_16x16x32_bf16 v[12:15], v[150:153], v[202:205], v[12:15]
	s_setprio 0
	s_setprio 1
	v_mfma_f32_16x16x32_bf16 v[56:59], v[154:157], v[170:173], v[56:59]
	v_mfma_f32_16x16x32_bf16 v[52:55], v[162:165], v[170:173], v[52:55]
	v_mfma_f32_16x16x32_bf16 v[40:43], v[154:157], v[178:181], v[40:43]
	v_mfma_f32_16x16x32_bf16 v[36:39], v[162:165], v[178:181], v[36:39]
	v_mfma_f32_16x16x32_bf16 v[24:27], v[154:157], v[186:189], v[24:27]
	v_mfma_f32_16x16x32_bf16 v[20:23], v[162:165], v[186:189], v[20:23]
	v_mfma_f32_16x16x32_bf16 v[8:11], v[154:157], v[194:197], v[8:11]
	v_mfma_f32_16x16x32_bf16 v[4:7], v[162:165], v[194:197], v[4:7]
	v_mfma_f32_16x16x32_bf16 v[56:59], v[158:161], v[174:177], v[56:59]
	v_mfma_f32_16x16x32_bf16 v[52:55], v[166:169], v[174:177], v[52:55]
	v_mfma_f32_16x16x32_bf16 v[40:43], v[158:161], v[182:185], v[40:43]
	v_mfma_f32_16x16x32_bf16 v[36:39], v[166:169], v[182:185], v[36:39]
	v_mfma_f32_16x16x32_bf16 v[24:27], v[158:161], v[190:193], v[24:27]
	v_mfma_f32_16x16x32_bf16 v[20:23], v[166:169], v[190:193], v[20:23]
	v_mfma_f32_16x16x32_bf16 v[8:11], v[158:161], v[202:205], v[8:11]
	v_mfma_f32_16x16x32_bf16 v[4:7], v[166:169], v[202:205], v[4:7]
	s_setprio 0
	s_barrier
	s_cbranch_scc0 .LBB0_1309
